# GEMM K-loops: pre-barrier vmcnt and lgkmcnt waits merged into one instruction, redundant post-barrier lgkmcnt(0) dropped
# baseline (speedup 1.0000x reference)
; #define PG8_STAGE(bufoff, gbase, voff) do { _Pragma("unroll") for (int _i = 0; _i < 2; ++_i) \
;         __builtin_amdgcn_global_load_lds((const unsigned*)((const char*)(gbase) + (voff)[_i]), (PG8_LAS unsigned*)(lds + (bufoff) + ldsw + _i * 8192), 16, 0, 0); } while (0)
; #define PG8_LDA(dst, b, h) do { _Pragma("unroll") for (int m = 0; m < 4; ++m) _Pragma("unroll") for (int k = 0; k < 2; ++k) dst[m][k] = *(const PG8_LAS bf16x8*)(lds + PG8_SA(b, h) + aoff + m * 2048 + k * 1024); } while (0)
; #define PG8_LDB(dst, b, h) do { _Pragma("unroll") for (int n = 0; n < 2; ++n) _Pragma("unroll") for (int k = 0; k < 2; ++k) dst[n][k] = *(const PG8_LAS bf16x8*)(lds + PG8_SB(b, h) + boff + n * 2048 + k * 1024); } while (0)
; #define PG8_WAIT_V(n) asm volatile("s_waitcnt vmcnt(" #n ")" ::: "memory")
; #define PG8_WAIT_L(n) asm volatile("s_waitcnt lgkmcnt(" #n ")" ::: "memory")
; #define PG8_BAR __builtin_amdgcn_s_barrier()
; #define PG8_SCHED __builtin_amdgcn_sched_barrier(0)
; template <class Epi, class Sched, bool ALIGN_EPI = false, bool SP2 = false>
; __device__ __forceinline__ void gemm_phase(PG8_LAS unsigned char* lds, const Gemm g, const Sched& S, const Epi& E, int wave_in) {
;     ...
;         const char* nA = has_next ? (const char*)g.A + (size_t)nxt.pm * tstepA : cA; const char* nB = has_next ? (const char*)g.Bt + (size_t)nxt.pn * tstep : cB;
;         for (int t = 0; t < nt; t += 2) {
;             const bool last = (t == nt - 2);
;             const char* a1 = cA + (size_t)(t + 1) * kstep;
;             const char* a2 = last ? nA : cA + (size_t)(t + 2) * kstep; const char* b2 = last ? nB : cB + (size_t)(t + 2) * kstep;
;             const char* a3 = a2 + kstep; const char* b3 = b2 + kstep;
;             if (last && has_next) S.a_ready(nxt);
;             if constexpr (SP2) {
;             PG8_LDB(B0, 0, 0); PG8_LDB(B1, 0, 1); PG8_SCHED; PG8_LDA(At, 0, 0); PG8_STAGE(PG8_SA(1, 1), a1 + hstepA, voffA);
;             PG8_WAIT_V(8); PG8_WAIT_L(0); PG8_BAR; PG8_MMA(0, 0, At, B0); PG8_MMA(0, 1, At, B1); PG8_BAR; PG8_SCHED;
;             PG8_LDA(At, 0, 1); PG8_STAGE(PG8_SB(0, 0), b2, voffB); PG8_STAGE(PG8_SB(0, 1), b2 + hstep, voffB); PG8_STAGE(PG8_SA(0, 0), a2, voffA);
;             PG8_WAIT_V(8); PG8_WAIT_L(0); PG8_BAR; PG8_MMA(1, 0, At, B0); PG8_MMA(1, 1, At, B1); PG8_BAR; PG8_SCHED;
.LBB0_43:
	s_add_u32 s50, s48, 0xfff80080
	s_addc_u32 s51, s49, -1
	s_add_i32 s72, 0, 0x10000
	s_cmp_eq_u32 s71, 28
	s_cselect_b32 s53, s43, s51
	s_cselect_b32 s52, s67, s50
	s_cselect_b32 s51, s41, s70
	s_cselect_b32 s50, s68, s69
	s_add_i32 s74, 0, 0x14000
	v_add_u32_e32 v118, s72, v214
	v_add_u32_e32 v178, s74, v214
	ds_read_b128 v[106:109], v118
	ds_read_b128 v[110:113], v118 offset:1024
	ds_read_b128 v[114:117], v118 offset:2048
	ds_read_b128 v[118:121], v118 offset:3072
	ds_read_b128 v[122:125], v178
	ds_read_b128 v[126:129], v178 offset:1024
	ds_read_b128 v[130:133], v178 offset:2048
	ds_read_b128 v[178:181], v178 offset:3072
	v_lshl_add_u64 v[238:239], s[48:49], 0, v[174:175]
	s_add_i32 m0, s58, 0xc000
	ds_read_b128 v[182:185], v217
	ds_read_b128 v[186:189], v217 offset:1024
	ds_read_b128 v[190:193], v217 offset:2048
	ds_read_b128 v[218:221], v217 offset:3072
	ds_read_b128 v[222:225], v217 offset:4096
	ds_read_b128 v[226:229], v217 offset:5120
	ds_read_b128 v[230:233], v217 offset:6144
	ds_read_b128 v[234:237], v217 offset:7168
	global_load_lds_dwordx4 v[238:239], off
	v_lshl_add_u64 v[238:239], s[48:49], 0, v[176:177]
	s_add_i32 m0, s58, 0xe000
	s_nop 0
	global_load_lds_dwordx4 v[238:239], off
	s_waitcnt vmcnt(8) lgkmcnt(0)
	s_barrier
	v_mfma_f32_16x16x32_bf16 v[154:157], v[106:109], v[182:185], v[154:157]
	v_mfma_f32_16x16x32_bf16 v[62:65], v[114:117], v[182:185], v[62:65]
	v_mfma_f32_16x16x32_bf16 v[150:153], v[106:109], v[190:193], v[150:153]
	v_mfma_f32_16x16x32_bf16 v[54:57], v[114:117], v[190:193], v[54:57]
	v_mfma_f32_16x16x32_bf16 v[142:145], v[106:109], v[222:225], v[142:145]
	v_mfma_f32_16x16x32_bf16 v[46:49], v[114:117], v[222:225], v[46:49]
	v_mfma_f32_16x16x32_bf16 v[102:105], v[106:109], v[230:233], v[102:105]
	v_mfma_f32_16x16x32_bf16 v[38:41], v[114:117], v[230:233], v[38:41]
	v_mfma_f32_16x16x32_bf16 v[154:157], v[110:113], v[186:189], v[154:157]
	v_mfma_f32_16x16x32_bf16 v[62:65], v[118:121], v[186:189], v[62:65]
	v_mfma_f32_16x16x32_bf16 v[150:153], v[110:113], v[218:221], v[150:153]
	v_mfma_f32_16x16x32_bf16 v[54:57], v[118:121], v[218:221], v[54:57]
	v_mfma_f32_16x16x32_bf16 v[142:145], v[110:113], v[226:229], v[142:145]
	v_mfma_f32_16x16x32_bf16 v[46:49], v[118:121], v[226:229], v[46:49]
	v_mfma_f32_16x16x32_bf16 v[102:105], v[110:113], v[234:237], v[102:105]
	v_mfma_f32_16x16x32_bf16 v[38:41], v[118:121], v[234:237], v[38:41]
	v_mfma_f32_16x16x32_bf16 v[134:137], v[122:125], v[182:185], v[134:137]
	v_mfma_f32_16x16x32_bf16 v[58:61], v[130:133], v[182:185], v[58:61]
	v_mfma_f32_16x16x32_bf16 v[146:149], v[122:125], v[190:193], v[146:149]
	v_mfma_f32_16x16x32_bf16 v[50:53], v[130:133], v[190:193], v[50:53]
	v_mfma_f32_16x16x32_bf16 v[138:141], v[122:125], v[222:225], v[138:141]
	v_mfma_f32_16x16x32_bf16 v[42:45], v[130:133], v[222:225], v[42:45]
	v_mfma_f32_16x16x32_bf16 v[98:101], v[122:125], v[230:233], v[98:101]
	v_mfma_f32_16x16x32_bf16 v[34:37], v[130:133], v[230:233], v[34:37]
	v_mfma_f32_16x16x32_bf16 v[134:137], v[126:129], v[186:189], v[134:137]
	v_mfma_f32_16x16x32_bf16 v[58:61], v[178:181], v[186:189], v[58:61]
	v_mfma_f32_16x16x32_bf16 v[146:149], v[126:129], v[218:221], v[146:149]
	v_mfma_f32_16x16x32_bf16 v[50:53], v[178:181], v[218:221], v[50:53]
	v_mfma_f32_16x16x32_bf16 v[138:141], v[126:129], v[226:229], v[138:141]
	v_mfma_f32_16x16x32_bf16 v[42:45], v[178:181], v[226:229], v[42:45]
	v_mfma_f32_16x16x32_bf16 v[98:101], v[126:129], v[234:237], v[98:101]
	v_mfma_f32_16x16x32_bf16 v[34:37], v[178:181], v[234:237], v[34:37]
	s_barrier
	s_add_i32 s72, s72, s57
	v_lshl_add_u64 v[238:239], s[50:51], 0, v[0:1]
	s_mov_b32 m0, s72
	ds_read_b128 v[182:185], v217 offset:16384
	ds_read_b128 v[186:189], v217 offset:17408
	ds_read_b128 v[190:193], v217 offset:18432
	ds_read_b128 v[218:221], v217 offset:19456
	ds_read_b128 v[222:225], v217 offset:20480
	ds_read_b128 v[226:229], v217 offset:21504
	ds_read_b128 v[230:233], v217 offset:22528
	ds_read_b128 v[234:237], v217 offset:23552
	global_load_lds_dwordx4 v[238:239], off
	s_add_i32 m0, s72, 0x2000
	s_add_u32 s72, s50, 0x80000
	v_lshl_add_u64 v[240:241], s[50:51], 0, v[168:169]
	s_addc_u32 s73, s51, 0
	s_add_i32 s74, s74, s57
	global_load_lds_dwordx4 v[240:241], off
	v_lshl_add_u64 v[242:243], s[72:73], 0, v[0:1]
	s_mov_b32 m0, s74
	v_lshl_add_u64 v[244:245], s[52:53], 0, v[170:171]
	global_load_lds_dwordx4 v[242:243], off
	v_lshl_add_u64 v[242:243], s[72:73], 0, v[168:169]
	s_add_i32 m0, s74, 0x2000
	s_nop 0
	global_load_lds_dwordx4 v[242:243], off
	v_lshl_add_u64 v[242:243], s[52:53], 0, v[172:173]
	s_mov_b32 m0, s58
	s_nop 0
	global_load_lds_dwordx4 v[242:243], off
	s_mov_b32 m0, s59
	s_nop 0
	global_load_lds_dwordx4 v[244:245], off
	s_waitcnt vmcnt(8) lgkmcnt(0)
	s_barrier
; #define PG8_STAGE(bufoff, gbase, voff) do { _Pragma("unroll") for (int _i = 0; _i < 2; ++_i) \
;         __builtin_amdgcn_global_load_lds((const unsigned*)((const char*)(gbase) + (voff)[_i]), (PG8_LAS unsigned*)(lds + (bufoff) + ldsw + _i * 8192), 16, 0, 0); } while (0)
; #define PG8_LDA(dst, b, h) do { _Pragma("unroll") for (int m = 0; m < 4; ++m) _Pragma("unroll") for (int k = 0; k < 2; ++k) dst[m][k] = *(const PG8_LAS bf16x8*)(lds + PG8_SA(b, h) + aoff + m * 2048 + k * 1024); } while (0)
; #define PG8_LDB(dst, b, h) do { _Pragma("unroll") for (int n = 0; n < 2; ++n) _Pragma("unroll") for (int k = 0; k < 2; ++k) dst[n][k] = *(const PG8_LAS bf16x8*)(lds + PG8_SB(b, h) + boff + n * 2048 + k * 1024); } while (0)
; #define PG8_MMA(ai, bj, At, Bt) do { __builtin_amdgcn_s_setprio(1); _Pragma("unroll") for (int m = 0; m < 4; ++m) _Pragma("unroll") for (int n = 0; n < 2; ++n) _Pragma("unroll") for (int k = 0; k < 2; ++k) \
;         acc[ai][bj][m][n] = __builtin_amdgcn_mfma_f32_16x16x32_bf16(Bt[n][k], At[m][k], acc[ai][bj][m][n], 0, 0, 0); __builtin_amdgcn_s_setprio(0); } while (0)
; #define PG8_WAIT_V(n) asm volatile("s_waitcnt vmcnt(" #n ")" ::: "memory")
; #define PG8_WAIT_L(n) asm volatile("s_waitcnt lgkmcnt(" #n ")" ::: "memory")
; #define PG8_BAR __builtin_amdgcn_s_barrier()
; #define PG8_SCHED __builtin_amdgcn_sched_barrier(0)
; template <class Epi, class Sched, bool ALIGN_EPI = false, bool SP2 = false>
; __device__ __forceinline__ void gemm_phase(PG8_LAS unsigned char* lds, const Gemm g, const Sched& S, const Epi& E, int wave_in) {
;     ...
;             PG8_WAIT_V(8); PG8_WAIT_L(0); PG8_BAR; PG8_MMA(1, 0, At, B0); PG8_MMA(1, 1, At, B1); PG8_BAR; PG8_SCHED;
;             PG8_LDB(B0, 1, 0); PG8_LDB(B1, 1, 1); PG8_SCHED; PG8_LDA(At, 1, 0); PG8_STAGE(PG8_SA(0, 1), a2 + hstepA, voffA);
;             PG8_WAIT_V(8); PG8_WAIT_L(0); PG8_BAR; PG8_MMA(0, 0, At, B0); PG8_MMA(0, 1, At, B1); PG8_BAR; PG8_SCHED;
	v_mfma_f32_16x16x32_bf16 v[94:97], v[106:109], v[182:185], v[94:97]
	v_mfma_f32_16x16x32_bf16 v[30:33], v[114:117], v[182:185], v[30:33]
	v_mfma_f32_16x16x32_bf16 v[86:89], v[106:109], v[190:193], v[86:89]
	v_mfma_f32_16x16x32_bf16 v[22:25], v[114:117], v[190:193], v[22:25]
	v_mfma_f32_16x16x32_bf16 v[78:81], v[106:109], v[222:225], v[78:81]
	v_mfma_f32_16x16x32_bf16 v[14:17], v[114:117], v[222:225], v[14:17]
	v_mfma_f32_16x16x32_bf16 v[70:73], v[106:109], v[230:233], v[70:73]
	v_mfma_f32_16x16x32_bf16 v[6:9], v[114:117], v[230:233], v[6:9]
	v_mfma_f32_16x16x32_bf16 v[94:97], v[110:113], v[186:189], v[94:97]
	v_mfma_f32_16x16x32_bf16 v[30:33], v[118:121], v[186:189], v[30:33]
	v_mfma_f32_16x16x32_bf16 v[86:89], v[110:113], v[218:221], v[86:89]
	v_mfma_f32_16x16x32_bf16 v[22:25], v[118:121], v[218:221], v[22:25]
	v_mfma_f32_16x16x32_bf16 v[78:81], v[110:113], v[226:229], v[78:81]
	v_mfma_f32_16x16x32_bf16 v[14:17], v[118:121], v[226:229], v[14:17]
	v_mfma_f32_16x16x32_bf16 v[70:73], v[110:113], v[234:237], v[70:73]
	v_mfma_f32_16x16x32_bf16 v[6:9], v[118:121], v[234:237], v[6:9]
	v_mfma_f32_16x16x32_bf16 v[90:93], v[122:125], v[182:185], v[90:93]
	v_mfma_f32_16x16x32_bf16 v[26:29], v[130:133], v[182:185], v[26:29]
	v_mfma_f32_16x16x32_bf16 v[82:85], v[122:125], v[190:193], v[82:85]
	v_mfma_f32_16x16x32_bf16 v[18:21], v[130:133], v[190:193], v[18:21]
	v_mfma_f32_16x16x32_bf16 v[74:77], v[122:125], v[222:225], v[74:77]
	v_mfma_f32_16x16x32_bf16 v[10:13], v[130:133], v[222:225], v[10:13]
	v_mfma_f32_16x16x32_bf16 v[66:69], v[122:125], v[230:233], v[66:69]
	v_mfma_f32_16x16x32_bf16 v[2:5], v[130:133], v[230:233], v[2:5]
	v_mfma_f32_16x16x32_bf16 v[90:93], v[126:129], v[186:189], v[90:93]
	v_mfma_f32_16x16x32_bf16 v[26:29], v[178:181], v[186:189], v[26:29]
	v_mfma_f32_16x16x32_bf16 v[82:85], v[126:129], v[218:221], v[82:85]
	v_mfma_f32_16x16x32_bf16 v[18:21], v[178:181], v[218:221], v[18:21]
	v_mfma_f32_16x16x32_bf16 v[74:77], v[126:129], v[226:229], v[74:77]
	v_mfma_f32_16x16x32_bf16 v[10:13], v[178:181], v[226:229], v[10:13]
	v_mfma_f32_16x16x32_bf16 v[66:69], v[126:129], v[234:237], v[66:69]
	v_mfma_f32_16x16x32_bf16 v[2:5], v[178:181], v[234:237], v[2:5]
	s_barrier
	s_add_i32 s72, 0, 0x18000
	s_add_i32 s73, 0, 0x1c000
	v_add_u32_e32 v118, s72, v214
	v_add_u32_e32 v178, s73, v214
	ds_read_b128 v[106:109], v118
	ds_read_b128 v[110:113], v118 offset:1024
	ds_read_b128 v[114:117], v118 offset:2048
	ds_read_b128 v[118:121], v118 offset:3072
	ds_read_b128 v[122:125], v178
	ds_read_b128 v[126:129], v178 offset:1024
	ds_read_b128 v[130:133], v178 offset:2048
	ds_read_b128 v[178:181], v178 offset:3072
	s_add_u32 s52, s52, 0x80000
	s_addc_u32 s53, s53, 0
	s_mov_b32 m0, s60
	v_lshl_add_u64 v[246:247], s[52:53], 0, v[172:173]
	ds_read_b128 v[182:185], v217 offset:32768
	ds_read_b128 v[186:189], v217 offset:33792
	ds_read_b128 v[190:193], v217 offset:34816
	ds_read_b128 v[218:221], v217 offset:35840
	ds_read_b128 v[222:225], v217 offset:36864
	ds_read_b128 v[226:229], v217 offset:37888
	ds_read_b128 v[230:233], v217 offset:38912
	ds_read_b128 v[234:237], v217 offset:39936
	global_load_lds_dwordx4 v[246:247], off
	v_lshl_add_u64 v[246:247], s[52:53], 0, v[170:171]
	s_mov_b32 m0, s61
	s_nop 0
	global_load_lds_dwordx4 v[246:247], off
	s_waitcnt vmcnt(8) lgkmcnt(0)
	s_barrier
	v_mfma_f32_16x16x32_bf16 v[154:157], v[106:109], v[182:185], v[154:157]
	v_mfma_f32_16x16x32_bf16 v[62:65], v[114:117], v[182:185], v[62:65]
	v_mfma_f32_16x16x32_bf16 v[150:153], v[106:109], v[190:193], v[150:153]
	v_mfma_f32_16x16x32_bf16 v[54:57], v[114:117], v[190:193], v[54:57]
	v_mfma_f32_16x16x32_bf16 v[142:145], v[106:109], v[222:225], v[142:145]
	v_mfma_f32_16x16x32_bf16 v[46:49], v[114:117], v[222:225], v[46:49]
	v_mfma_f32_16x16x32_bf16 v[102:105], v[106:109], v[230:233], v[102:105]
	v_mfma_f32_16x16x32_bf16 v[38:41], v[114:117], v[230:233], v[38:41]
	v_mfma_f32_16x16x32_bf16 v[154:157], v[110:113], v[186:189], v[154:157]
	v_mfma_f32_16x16x32_bf16 v[62:65], v[118:121], v[186:189], v[62:65]
	v_mfma_f32_16x16x32_bf16 v[150:153], v[110:113], v[218:221], v[150:153]
	v_mfma_f32_16x16x32_bf16 v[54:57], v[118:121], v[218:221], v[54:57]
	v_mfma_f32_16x16x32_bf16 v[142:145], v[110:113], v[226:229], v[142:145]
	v_mfma_f32_16x16x32_bf16 v[46:49], v[118:121], v[226:229], v[46:49]
	v_mfma_f32_16x16x32_bf16 v[102:105], v[110:113], v[234:237], v[102:105]
	v_mfma_f32_16x16x32_bf16 v[38:41], v[118:121], v[234:237], v[38:41]
	v_mfma_f32_16x16x32_bf16 v[134:137], v[122:125], v[182:185], v[134:137]
	v_mfma_f32_16x16x32_bf16 v[58:61], v[130:133], v[182:185], v[58:61]
	v_mfma_f32_16x16x32_bf16 v[146:149], v[122:125], v[190:193], v[146:149]
	v_mfma_f32_16x16x32_bf16 v[50:53], v[130:133], v[190:193], v[50:53]
	v_mfma_f32_16x16x32_bf16 v[138:141], v[122:125], v[222:225], v[138:141]
	v_mfma_f32_16x16x32_bf16 v[42:45], v[130:133], v[222:225], v[42:45]
	v_mfma_f32_16x16x32_bf16 v[98:101], v[122:125], v[230:233], v[98:101]
	v_mfma_f32_16x16x32_bf16 v[34:37], v[130:133], v[230:233], v[34:37]
	v_mfma_f32_16x16x32_bf16 v[134:137], v[126:129], v[186:189], v[134:137]
	v_mfma_f32_16x16x32_bf16 v[58:61], v[178:181], v[186:189], v[58:61]
	v_mfma_f32_16x16x32_bf16 v[146:149], v[126:129], v[218:221], v[146:149]
	v_mfma_f32_16x16x32_bf16 v[50:53], v[178:181], v[218:221], v[50:53]
	v_mfma_f32_16x16x32_bf16 v[138:141], v[126:129], v[226:229], v[138:141]
	v_mfma_f32_16x16x32_bf16 v[42:45], v[178:181], v[226:229], v[42:45]
	v_mfma_f32_16x16x32_bf16 v[98:101], v[126:129], v[234:237], v[98:101]
	v_mfma_f32_16x16x32_bf16 v[34:37], v[178:181], v[234:237], v[34:37]
	s_barrier
; #define PG8_STAGE(bufoff, gbase, voff) do { _Pragma("unroll") for (int _i = 0; _i < 2; ++_i) \
;         __builtin_amdgcn_global_load_lds((const unsigned*)((const char*)(gbase) + (voff)[_i]), (PG8_LAS unsigned*)(lds + (bufoff) + ldsw + _i * 8192), 16, 0, 0); } while (0)
; #define PG8_LDA(dst, b, h) do { _Pragma("unroll") for (int m = 0; m < 4; ++m) _Pragma("unroll") for (int k = 0; k < 2; ++k) dst[m][k] = *(const PG8_LAS bf16x8*)(lds + PG8_SA(b, h) + aoff + m * 2048 + k * 1024); } while (0)
; #define PG8_MMA(ai, bj, At, Bt) do { __builtin_amdgcn_s_setprio(1); _Pragma("unroll") for (int m = 0; m < 4; ++m) _Pragma("unroll") for (int n = 0; n < 2; ++n) _Pragma("unroll") for (int k = 0; k < 2; ++k) \
;         acc[ai][bj][m][n] = __builtin_amdgcn_mfma_f32_16x16x32_bf16(Bt[n][k], At[m][k], acc[ai][bj][m][n], 0, 0, 0); __builtin_amdgcn_s_setprio(0); } while (0)
; #define PG8_WAIT_V(n) asm volatile("s_waitcnt vmcnt(" #n ")" ::: "memory")
; #define PG8_WAIT_L(n) asm volatile("s_waitcnt lgkmcnt(" #n ")" ::: "memory")
; #define PG8_BAR __builtin_amdgcn_s_barrier()
; #define PG8_SCHED __builtin_amdgcn_sched_barrier(0)
; template <class Epi, class Sched, bool ALIGN_EPI = false, bool SP2 = false>
; __device__ __forceinline__ void gemm_phase(PG8_LAS unsigned char* lds, const Gemm g, const Sched& S, const Epi& E, int wave_in) {
;     ...
;         for (int t = 0; t < nt; t += 2) {
;             const bool last = (t == nt - 2);
;             const char* a1 = cA + (size_t)(t + 1) * kstep;
;             const char* a2 = last ? nA : cA + (size_t)(t + 2) * kstep; const char* b2 = last ? nB : cB + (size_t)(t + 2) * kstep;
;     ...
;             PG8_LDA(At, 1, 1); PG8_STAGE(PG8_SB(1, 0), b3, voffB); PG8_STAGE(PG8_SB(1, 1), b3 + hstep, voffB); PG8_STAGE(PG8_SA(1, 0), a3, voffA);
;             PG8_WAIT_V(8); PG8_WAIT_L(0); PG8_BAR; PG8_MMA(1, 0, At, B0); PG8_MMA(1, 1, At, B1); PG8_BAR; PG8_SCHED;
	s_add_i32 s52, s72, s57
	v_lshl_add_u64 v[238:239], v[238:239], 0, s[84:85]
	s_mov_b32 m0, s52
	ds_read_b128 v[182:185], v217 offset:49152
	ds_read_b128 v[186:189], v217 offset:50176
	ds_read_b128 v[190:193], v217 offset:51200
	ds_read_b128 v[218:221], v217 offset:52224
	ds_read_b128 v[222:225], v217 offset:53248
	ds_read_b128 v[226:229], v217 offset:54272
	ds_read_b128 v[230:233], v217 offset:55296
	ds_read_b128 v[234:237], v217 offset:56320
	global_load_lds_dwordx4 v[238:239], off
	s_add_i32 m0, s52, 0x2000
	s_add_u32 s50, s50, 0x80080
	v_lshl_add_u64 v[238:239], v[240:241], 0, s[84:85]
	s_addc_u32 s51, s51, 0
	s_add_i32 s52, s73, s57
	global_load_lds_dwordx4 v[238:239], off
	v_lshl_add_u64 v[238:239], s[50:51], 0, v[0:1]
	s_mov_b32 m0, s52
	s_nop 0
	global_load_lds_dwordx4 v[238:239], off
	v_lshl_add_u64 v[238:239], s[50:51], 0, v[168:169]
	s_add_i32 m0, s52, 0x2000
	s_nop 0
	global_load_lds_dwordx4 v[238:239], off
	v_lshl_add_u64 v[238:239], v[242:243], 0, s[84:85]
	s_mov_b32 m0, s62
	s_nop 0
	global_load_lds_dwordx4 v[238:239], off
	v_lshl_add_u64 v[238:239], v[244:245], 0, s[84:85]
	s_mov_b32 m0, s63
	s_nop 0
	global_load_lds_dwordx4 v[238:239], off
	s_waitcnt vmcnt(8) lgkmcnt(0)
	s_barrier
	v_mfma_f32_16x16x32_bf16 v[94:97], v[106:109], v[182:185], v[94:97]
	v_mfma_f32_16x16x32_bf16 v[30:33], v[114:117], v[182:185], v[30:33]
	v_mfma_f32_16x16x32_bf16 v[86:89], v[106:109], v[190:193], v[86:89]
	v_mfma_f32_16x16x32_bf16 v[22:25], v[114:117], v[190:193], v[22:25]
	v_mfma_f32_16x16x32_bf16 v[78:81], v[106:109], v[222:225], v[78:81]
	v_mfma_f32_16x16x32_bf16 v[14:17], v[114:117], v[222:225], v[14:17]
	v_mfma_f32_16x16x32_bf16 v[70:73], v[106:109], v[230:233], v[70:73]
	v_mfma_f32_16x16x32_bf16 v[6:9], v[114:117], v[230:233], v[6:9]
	v_mfma_f32_16x16x32_bf16 v[94:97], v[110:113], v[186:189], v[94:97]
	v_mfma_f32_16x16x32_bf16 v[30:33], v[118:121], v[186:189], v[30:33]
	v_mfma_f32_16x16x32_bf16 v[86:89], v[110:113], v[218:221], v[86:89]
	v_mfma_f32_16x16x32_bf16 v[22:25], v[118:121], v[218:221], v[22:25]
	v_mfma_f32_16x16x32_bf16 v[78:81], v[110:113], v[226:229], v[78:81]
	v_mfma_f32_16x16x32_bf16 v[14:17], v[118:121], v[226:229], v[14:17]
	v_mfma_f32_16x16x32_bf16 v[70:73], v[110:113], v[234:237], v[70:73]
	v_mfma_f32_16x16x32_bf16 v[6:9], v[118:121], v[234:237], v[6:9]
	v_mfma_f32_16x16x32_bf16 v[90:93], v[122:125], v[182:185], v[90:93]
	v_mfma_f32_16x16x32_bf16 v[26:29], v[130:133], v[182:185], v[26:29]
	v_mfma_f32_16x16x32_bf16 v[82:85], v[122:125], v[190:193], v[82:85]
	v_mfma_f32_16x16x32_bf16 v[18:21], v[130:133], v[190:193], v[18:21]
	v_mfma_f32_16x16x32_bf16 v[74:77], v[122:125], v[222:225], v[74:77]
	v_mfma_f32_16x16x32_bf16 v[10:13], v[130:133], v[222:225], v[10:13]
	v_mfma_f32_16x16x32_bf16 v[66:69], v[122:125], v[230:233], v[66:69]
	v_mfma_f32_16x16x32_bf16 v[2:5], v[130:133], v[230:233], v[2:5]
	v_mfma_f32_16x16x32_bf16 v[90:93], v[126:129], v[186:189], v[90:93]
	v_mfma_f32_16x16x32_bf16 v[26:29], v[178:181], v[186:189], v[26:29]
	v_mfma_f32_16x16x32_bf16 v[82:85], v[126:129], v[218:221], v[82:85]
	v_mfma_f32_16x16x32_bf16 v[18:21], v[178:181], v[218:221], v[18:21]
	v_mfma_f32_16x16x32_bf16 v[74:77], v[126:129], v[226:229], v[74:77]
	v_mfma_f32_16x16x32_bf16 v[10:13], v[178:181], v[226:229], v[10:13]
	v_mfma_f32_16x16x32_bf16 v[66:69], v[126:129], v[234:237], v[66:69]
	v_mfma_f32_16x16x32_bf16 v[2:5], v[178:181], v[234:237], v[2:5]
	s_barrier
	s_add_i32 s71, s71, 2
	s_add_u32 s48, s48, 0x100
	s_addc_u32 s49, s49, 0
	s_add_u32 s69, s69, 0x100
	s_addc_u32 s70, s70, 0
	s_cmp_gt_u32 s71, 29
	s_cbranch_scc0 .LBB0_43
	s_and_b64 vcc, exec, s[24:25]
	s_cbranch_vccz .LBB0_46
	s_barrier

; #define PG8_STAGE(bufoff, gbase, voff) do { _Pragma("unroll") for (int _i = 0; _i < 2; ++_i) \
;         __builtin_amdgcn_global_load_lds((const unsigned*)((const char*)(gbase) + (voff)[_i]), (PG8_LAS unsigned*)(lds + (bufoff) + ldsw + _i * 8192), 16, 0, 0); } while (0)
; #define PG8_LDA(dst, b, h) do { _Pragma("unroll") for (int m = 0; m < 4; ++m) _Pragma("unroll") for (int k = 0; k < 2; ++k) dst[m][k] = *(const PG8_LAS bf16x8*)(lds + PG8_SA(b, h) + aoff + m * 2048 + k * 1024); } while (0)
; #define PG8_LDB(dst, b, h) do { _Pragma("unroll") for (int n = 0; n < 2; ++n) _Pragma("unroll") for (int k = 0; k < 2; ++k) dst[n][k] = *(const PG8_LAS bf16x8*)(lds + PG8_SB(b, h) + boff + n * 2048 + k * 1024); } while (0)
; #define PG8_MMA(ai, bj, At, Bt) do { __builtin_amdgcn_s_setprio(1); _Pragma("unroll") for (int m = 0; m < 4; ++m) _Pragma("unroll") for (int n = 0; n < 2; ++n) _Pragma("unroll") for (int k = 0; k < 2; ++k) \
;         acc[ai][bj][m][n] = __builtin_amdgcn_mfma_f32_16x16x32_bf16(Bt[n][k], At[m][k], acc[ai][bj][m][n], 0, 0, 0); __builtin_amdgcn_s_setprio(0); } while (0)
; #define PG8_WAIT_V(n) asm volatile("s_waitcnt vmcnt(" #n ")" ::: "memory")
; #define PG8_WAIT_L(n) asm volatile("s_waitcnt lgkmcnt(" #n ")" ::: "memory")
; template <class Epi, class Sched, bool ALIGN_EPI = false, bool SP2 = false>
; __device__ __forceinline__ void gemm_phase(PG8_LAS unsigned char* lds, const Gemm g, const Sched& S, const Epi& E, int wave_in) {
;     ...
;             const bool last = (t == nt - 2);
;             const char* a1 = cA + (size_t)(t + 1) * kstep;
;             const char* a2 = last ? nA : cA + (size_t)(t + 2) * kstep; const char* b2 = last ? nB : cB + (size_t)(t + 2) * kstep;
;             const char* a3 = a2 + kstep; const char* b3 = b2 + kstep;
;             if (last && has_next) S.a_ready(nxt);
;             if constexpr (SP2) {
;             PG8_LDB(B0, 0, 0); PG8_LDB(B1, 0, 1); PG8_SCHED; PG8_LDA(At, 0, 0); PG8_STAGE(PG8_SA(1, 1), a1 + hstepA, voffA);
;             PG8_WAIT_V(8); PG8_WAIT_L(0); PG8_BAR; PG8_MMA(0, 0, At, B0); PG8_MMA(0, 1, At, B1); PG8_BAR; PG8_SCHED;
;             PG8_LDA(At, 0, 1); PG8_STAGE(PG8_SB(0, 0), b2, voffB); PG8_STAGE(PG8_SB(0, 1), b2 + hstep, voffB); PG8_STAGE(PG8_SA(0, 0), a2, voffA);
;             PG8_WAIT_V(8); PG8_WAIT_L(0); PG8_BAR; PG8_MMA(1, 0, At, B0); PG8_MMA(1, 1, At, B1); PG8_BAR; PG8_SCHED;
.LBB0_84:
	s_add_u32 s24, s22, 0xfff80080
	s_addc_u32 s25, s23, -1
	s_add_i32 s47, 0, 0x10000
	s_cmp_eq_u32 s46, 12
	s_cselect_b32 s27, s17, s25
	s_cselect_b32 s26, s42, s24
	v_add_u32_e32 v144, s47, v147
	s_cselect_b32 s25, s11, s45
	s_cselect_b32 s24, s43, s44
	s_add_i32 s50, 0, 0x14000
	ds_read_b128 v[140:143], v144
	ds_read_b128 v[150:153], v144 offset:1024
	ds_read_b128 v[154:157], v144 offset:2048
	ds_read_b128 v[168:171], v144 offset:3072
	v_add_u32_e32 v144, s50, v147
	ds_read_b128 v[172:175], v144
	ds_read_b128 v[176:179], v144 offset:1024
	ds_read_b128 v[180:183], v144 offset:2048
	ds_read_b128 v[184:187], v144 offset:3072
	v_lshl_add_u64 v[144:145], s[22:23], 0, v[136:137]
	s_add_i32 m0, s31, 0xc000
	ds_read_b128 v[188:191], v149
	ds_read_b128 v[212:215], v149 offset:1024
	ds_read_b128 v[216:219], v149 offset:2048
	ds_read_b128 v[220:223], v149 offset:3072
	ds_read_b128 v[224:227], v149 offset:4096
	ds_read_b128 v[228:231], v149 offset:5120
	ds_read_b128 v[232:235], v149 offset:6144
	ds_read_b128 v[236:239], v149 offset:7168
	global_load_lds_dwordx4 v[144:145], off
	v_lshl_add_u64 v[144:145], s[22:23], 0, v[138:139]
	s_add_i32 m0, s31, 0xe000
	s_nop 0
	global_load_lds_dwordx4 v[144:145], off
	s_waitcnt vmcnt(8) lgkmcnt(0)
	s_barrier
	v_mfma_f32_16x16x32_bf16 v[126:129], v[140:143], v[188:191], v[126:129]
	v_mfma_f32_16x16x32_bf16 v[122:125], v[154:157], v[188:191], v[122:125]
	v_mfma_f32_16x16x32_bf16 v[118:121], v[140:143], v[216:219], v[118:121]
	v_mfma_f32_16x16x32_bf16 v[106:109], v[154:157], v[216:219], v[106:109]
	v_mfma_f32_16x16x32_bf16 v[102:105], v[140:143], v[224:227], v[102:105]
	v_mfma_f32_16x16x32_bf16 v[90:93], v[154:157], v[224:227], v[90:93]
	v_mfma_f32_16x16x32_bf16 v[86:89], v[140:143], v[232:235], v[86:89]
	v_mfma_f32_16x16x32_bf16 v[74:77], v[154:157], v[232:235], v[74:77]
	v_mfma_f32_16x16x32_bf16 v[126:129], v[150:153], v[212:215], v[126:129]
	v_mfma_f32_16x16x32_bf16 v[122:125], v[168:171], v[212:215], v[122:125]
	v_mfma_f32_16x16x32_bf16 v[118:121], v[150:153], v[220:223], v[118:121]
	v_mfma_f32_16x16x32_bf16 v[106:109], v[168:171], v[220:223], v[106:109]
	v_mfma_f32_16x16x32_bf16 v[102:105], v[150:153], v[228:231], v[102:105]
	v_mfma_f32_16x16x32_bf16 v[90:93], v[168:171], v[228:231], v[90:93]
	v_mfma_f32_16x16x32_bf16 v[86:89], v[150:153], v[236:239], v[86:89]
	v_mfma_f32_16x16x32_bf16 v[74:77], v[168:171], v[236:239], v[74:77]
	v_mfma_f32_16x16x32_bf16 v[114:117], v[172:175], v[188:191], v[114:117]
	v_mfma_f32_16x16x32_bf16 v[110:113], v[180:183], v[188:191], v[110:113]
	v_mfma_f32_16x16x32_bf16 v[98:101], v[172:175], v[216:219], v[98:101]
	v_mfma_f32_16x16x32_bf16 v[94:97], v[180:183], v[216:219], v[94:97]
	v_mfma_f32_16x16x32_bf16 v[82:85], v[172:175], v[224:227], v[82:85]
	v_mfma_f32_16x16x32_bf16 v[78:81], v[180:183], v[224:227], v[78:81]
	v_mfma_f32_16x16x32_bf16 v[70:73], v[172:175], v[232:235], v[70:73]
	v_mfma_f32_16x16x32_bf16 v[66:69], v[180:183], v[232:235], v[66:69]
	v_mfma_f32_16x16x32_bf16 v[114:117], v[176:179], v[212:215], v[114:117]
	v_mfma_f32_16x16x32_bf16 v[110:113], v[184:187], v[212:215], v[110:113]
	v_mfma_f32_16x16x32_bf16 v[98:101], v[176:179], v[220:223], v[98:101]
	v_mfma_f32_16x16x32_bf16 v[94:97], v[184:187], v[220:223], v[94:97]
	v_mfma_f32_16x16x32_bf16 v[82:85], v[176:179], v[228:231], v[82:85]
	v_mfma_f32_16x16x32_bf16 v[78:81], v[184:187], v[228:231], v[78:81]
	v_mfma_f32_16x16x32_bf16 v[70:73], v[176:179], v[236:239], v[70:73]
	v_mfma_f32_16x16x32_bf16 v[66:69], v[184:187], v[236:239], v[66:69]
	s_barrier
	s_add_i32 s47, s47, s30
	v_lshl_add_u64 v[144:145], s[24:25], 0, v[0:1]
	s_mov_b32 m0, s47
	ds_read_b128 v[188:191], v149 offset:16384
	ds_read_b128 v[212:215], v149 offset:17408
	ds_read_b128 v[216:219], v149 offset:18432
	ds_read_b128 v[220:223], v149 offset:19456
	ds_read_b128 v[224:227], v149 offset:20480
	ds_read_b128 v[228:231], v149 offset:21504
	ds_read_b128 v[232:235], v149 offset:22528
	ds_read_b128 v[236:239], v149 offset:23552
	global_load_lds_dwordx4 v[144:145], off
	s_add_i32 m0, s47, 0x2000
	s_add_u32 s48, s24, 0x40000
	v_lshl_add_u64 v[192:193], s[24:25], 0, v[130:131]
	s_addc_u32 s49, s25, 0
	s_add_i32 s47, s50, s30
	global_load_lds_dwordx4 v[192:193], off
	v_lshl_add_u64 v[240:241], s[48:49], 0, v[0:1]
	s_mov_b32 m0, s47
	v_lshl_add_u64 v[242:243], s[26:27], 0, v[132:133]
	global_load_lds_dwordx4 v[240:241], off
	v_lshl_add_u64 v[240:241], s[48:49], 0, v[130:131]
	s_add_i32 m0, s47, 0x2000
	s_nop 0
	global_load_lds_dwordx4 v[240:241], off
	v_lshl_add_u64 v[240:241], s[26:27], 0, v[134:135]
	s_mov_b32 m0, s31
	s_nop 0
	global_load_lds_dwordx4 v[240:241], off
	s_mov_b32 m0, s34
	s_nop 0
	global_load_lds_dwordx4 v[242:243], off
	s_waitcnt vmcnt(8) lgkmcnt(0)
	s_barrier
; #define PG8_STAGE(bufoff, gbase, voff) do { _Pragma("unroll") for (int _i = 0; _i < 2; ++_i) \
;         __builtin_amdgcn_global_load_lds((const unsigned*)((const char*)(gbase) + (voff)[_i]), (PG8_LAS unsigned*)(lds + (bufoff) + ldsw + _i * 8192), 16, 0, 0); } while (0)
; #define PG8_LDA(dst, b, h) do { _Pragma("unroll") for (int m = 0; m < 4; ++m) _Pragma("unroll") for (int k = 0; k < 2; ++k) dst[m][k] = *(const PG8_LAS bf16x8*)(lds + PG8_SA(b, h) + aoff + m * 2048 + k * 1024); } while (0)
; #define PG8_LDB(dst, b, h) do { _Pragma("unroll") for (int n = 0; n < 2; ++n) _Pragma("unroll") for (int k = 0; k < 2; ++k) dst[n][k] = *(const PG8_LAS bf16x8*)(lds + PG8_SB(b, h) + boff + n * 2048 + k * 1024); } while (0)
; #define PG8_MMA(ai, bj, At, Bt) do { __builtin_amdgcn_s_setprio(1); _Pragma("unroll") for (int m = 0; m < 4; ++m) _Pragma("unroll") for (int n = 0; n < 2; ++n) _Pragma("unroll") for (int k = 0; k < 2; ++k) \
;         acc[ai][bj][m][n] = __builtin_amdgcn_mfma_f32_16x16x32_bf16(Bt[n][k], At[m][k], acc[ai][bj][m][n], 0, 0, 0); __builtin_amdgcn_s_setprio(0); } while (0)
; #define PG8_WAIT_V(n) asm volatile("s_waitcnt vmcnt(" #n ")" ::: "memory")
; #define PG8_WAIT_L(n) asm volatile("s_waitcnt lgkmcnt(" #n ")" ::: "memory")
; #define PG8_BAR __builtin_amdgcn_s_barrier()
; #define PG8_SCHED __builtin_amdgcn_sched_barrier(0)
; template <class Epi, class Sched, bool ALIGN_EPI = false, bool SP2 = false>
; __device__ __forceinline__ void gemm_phase(PG8_LAS unsigned char* lds, const Gemm g, const Sched& S, const Epi& E, int wave_in) {
;     ...
;             PG8_WAIT_V(8); PG8_WAIT_L(0); PG8_BAR; PG8_MMA(1, 0, At, B0); PG8_MMA(1, 1, At, B1); PG8_BAR; PG8_SCHED;
;             PG8_LDB(B0, 1, 0); PG8_LDB(B1, 1, 1); PG8_SCHED; PG8_LDA(At, 1, 0); PG8_STAGE(PG8_SA(0, 1), a2 + hstepA, voffA);
;             PG8_WAIT_V(8); PG8_WAIT_L(0); PG8_BAR; PG8_MMA(0, 0, At, B0); PG8_MMA(0, 1, At, B1); PG8_BAR; PG8_SCHED;
	v_mfma_f32_16x16x32_bf16 v[62:65], v[140:143], v[188:191], v[62:65]
	v_mfma_f32_16x16x32_bf16 v[58:61], v[154:157], v[188:191], v[58:61]
	v_mfma_f32_16x16x32_bf16 v[54:57], v[140:143], v[216:219], v[54:57]
	v_mfma_f32_16x16x32_bf16 v[42:45], v[154:157], v[216:219], v[42:45]
	v_mfma_f32_16x16x32_bf16 v[38:41], v[140:143], v[224:227], v[38:41]
	v_mfma_f32_16x16x32_bf16 v[26:29], v[154:157], v[224:227], v[26:29]
	v_mfma_f32_16x16x32_bf16 v[22:25], v[140:143], v[232:235], v[22:25]
	v_mfma_f32_16x16x32_bf16 v[10:13], v[154:157], v[232:235], v[10:13]
	v_mfma_f32_16x16x32_bf16 v[62:65], v[150:153], v[212:215], v[62:65]
	v_mfma_f32_16x16x32_bf16 v[58:61], v[168:171], v[212:215], v[58:61]
	v_mfma_f32_16x16x32_bf16 v[54:57], v[150:153], v[220:223], v[54:57]
	v_mfma_f32_16x16x32_bf16 v[42:45], v[168:171], v[220:223], v[42:45]
	v_mfma_f32_16x16x32_bf16 v[38:41], v[150:153], v[228:231], v[38:41]
	v_mfma_f32_16x16x32_bf16 v[26:29], v[168:171], v[228:231], v[26:29]
	v_mfma_f32_16x16x32_bf16 v[22:25], v[150:153], v[236:239], v[22:25]
	v_mfma_f32_16x16x32_bf16 v[10:13], v[168:171], v[236:239], v[10:13]
	v_mfma_f32_16x16x32_bf16 v[50:53], v[172:175], v[188:191], v[50:53]
	v_mfma_f32_16x16x32_bf16 v[46:49], v[180:183], v[188:191], v[46:49]
	v_mfma_f32_16x16x32_bf16 v[34:37], v[172:175], v[216:219], v[34:37]
	v_mfma_f32_16x16x32_bf16 v[30:33], v[180:183], v[216:219], v[30:33]
	v_mfma_f32_16x16x32_bf16 v[18:21], v[172:175], v[224:227], v[18:21]
	v_mfma_f32_16x16x32_bf16 v[14:17], v[180:183], v[224:227], v[14:17]
	v_mfma_f32_16x16x32_bf16 v[6:9], v[172:175], v[232:235], v[6:9]
	v_mfma_f32_16x16x32_bf16 v[2:5], v[180:183], v[232:235], v[2:5]
	v_mfma_f32_16x16x32_bf16 v[50:53], v[176:179], v[212:215], v[50:53]
	v_mfma_f32_16x16x32_bf16 v[46:49], v[184:187], v[212:215], v[46:49]
	v_mfma_f32_16x16x32_bf16 v[34:37], v[176:179], v[220:223], v[34:37]
	v_mfma_f32_16x16x32_bf16 v[30:33], v[184:187], v[220:223], v[30:33]
	v_mfma_f32_16x16x32_bf16 v[18:21], v[176:179], v[228:231], v[18:21]
	v_mfma_f32_16x16x32_bf16 v[14:17], v[184:187], v[228:231], v[14:17]
	v_mfma_f32_16x16x32_bf16 v[6:9], v[176:179], v[236:239], v[6:9]
	v_mfma_f32_16x16x32_bf16 v[2:5], v[184:187], v[236:239], v[2:5]
	s_barrier
	s_add_i32 s47, 0, 0x18000
	s_add_i32 s48, 0, 0x1c000
	v_add_u32_e32 v168, s47, v147
	v_add_u32_e32 v184, s48, v147
	ds_read_b128 v[140:143], v168
	ds_read_b128 v[150:153], v168 offset:1024
	ds_read_b128 v[154:157], v168 offset:2048
	ds_read_b128 v[168:171], v168 offset:3072
	ds_read_b128 v[172:175], v184
	ds_read_b128 v[176:179], v184 offset:1024
	ds_read_b128 v[180:183], v184 offset:2048
	ds_read_b128 v[184:187], v184 offset:3072
	s_add_u32 s26, s26, 0x80000
	s_addc_u32 s27, s27, 0
	s_mov_b32 m0, s35
	v_lshl_add_u64 v[244:245], s[26:27], 0, v[134:135]
	ds_read_b128 v[188:191], v149 offset:32768
	ds_read_b128 v[212:215], v149 offset:33792
	ds_read_b128 v[216:219], v149 offset:34816
	ds_read_b128 v[220:223], v149 offset:35840
	ds_read_b128 v[224:227], v149 offset:36864
	ds_read_b128 v[228:231], v149 offset:37888
	ds_read_b128 v[232:235], v149 offset:38912
	ds_read_b128 v[236:239], v149 offset:39936
	global_load_lds_dwordx4 v[244:245], off
	v_lshl_add_u64 v[244:245], s[26:27], 0, v[132:133]
	s_mov_b32 m0, s36
	s_nop 0
	global_load_lds_dwordx4 v[244:245], off
	s_waitcnt vmcnt(8) lgkmcnt(0)
	s_barrier
	v_mfma_f32_16x16x32_bf16 v[126:129], v[140:143], v[188:191], v[126:129]
	v_mfma_f32_16x16x32_bf16 v[122:125], v[154:157], v[188:191], v[122:125]
	v_mfma_f32_16x16x32_bf16 v[118:121], v[140:143], v[216:219], v[118:121]
	v_mfma_f32_16x16x32_bf16 v[106:109], v[154:157], v[216:219], v[106:109]
	v_mfma_f32_16x16x32_bf16 v[102:105], v[140:143], v[224:227], v[102:105]
	v_mfma_f32_16x16x32_bf16 v[90:93], v[154:157], v[224:227], v[90:93]
	v_mfma_f32_16x16x32_bf16 v[86:89], v[140:143], v[232:235], v[86:89]
	v_mfma_f32_16x16x32_bf16 v[74:77], v[154:157], v[232:235], v[74:77]
	v_mfma_f32_16x16x32_bf16 v[126:129], v[150:153], v[212:215], v[126:129]
	v_mfma_f32_16x16x32_bf16 v[122:125], v[168:171], v[212:215], v[122:125]
	v_mfma_f32_16x16x32_bf16 v[118:121], v[150:153], v[220:223], v[118:121]
	v_mfma_f32_16x16x32_bf16 v[106:109], v[168:171], v[220:223], v[106:109]
	v_mfma_f32_16x16x32_bf16 v[102:105], v[150:153], v[228:231], v[102:105]
	v_mfma_f32_16x16x32_bf16 v[90:93], v[168:171], v[228:231], v[90:93]
	v_mfma_f32_16x16x32_bf16 v[86:89], v[150:153], v[236:239], v[86:89]
	v_mfma_f32_16x16x32_bf16 v[74:77], v[168:171], v[236:239], v[74:77]
	v_mfma_f32_16x16x32_bf16 v[114:117], v[172:175], v[188:191], v[114:117]
	v_mfma_f32_16x16x32_bf16 v[110:113], v[180:183], v[188:191], v[110:113]
	v_mfma_f32_16x16x32_bf16 v[98:101], v[172:175], v[216:219], v[98:101]
	v_mfma_f32_16x16x32_bf16 v[94:97], v[180:183], v[216:219], v[94:97]
	v_mfma_f32_16x16x32_bf16 v[82:85], v[172:175], v[224:227], v[82:85]
	v_mfma_f32_16x16x32_bf16 v[78:81], v[180:183], v[224:227], v[78:81]
	v_mfma_f32_16x16x32_bf16 v[70:73], v[172:175], v[232:235], v[70:73]
	v_mfma_f32_16x16x32_bf16 v[66:69], v[180:183], v[232:235], v[66:69]
	v_mfma_f32_16x16x32_bf16 v[114:117], v[176:179], v[212:215], v[114:117]
	v_mfma_f32_16x16x32_bf16 v[110:113], v[184:187], v[212:215], v[110:113]
	v_mfma_f32_16x16x32_bf16 v[98:101], v[176:179], v[220:223], v[98:101]
	v_mfma_f32_16x16x32_bf16 v[94:97], v[184:187], v[220:223], v[94:97]
	v_mfma_f32_16x16x32_bf16 v[82:85], v[176:179], v[228:231], v[82:85]
	v_mfma_f32_16x16x32_bf16 v[78:81], v[184:187], v[228:231], v[78:81]
	v_mfma_f32_16x16x32_bf16 v[70:73], v[176:179], v[236:239], v[70:73]
	v_mfma_f32_16x16x32_bf16 v[66:69], v[184:187], v[236:239], v[66:69]
	s_barrier
; #define PG8_STAGE(bufoff, gbase, voff) do { _Pragma("unroll") for (int _i = 0; _i < 2; ++_i) \
;         __builtin_amdgcn_global_load_lds((const unsigned*)((const char*)(gbase) + (voff)[_i]), (PG8_LAS unsigned*)(lds + (bufoff) + ldsw + _i * 8192), 16, 0, 0); } while (0)
; #define PG8_LDA(dst, b, h) do { _Pragma("unroll") for (int m = 0; m < 4; ++m) _Pragma("unroll") for (int k = 0; k < 2; ++k) dst[m][k] = *(const PG8_LAS bf16x8*)(lds + PG8_SA(b, h) + aoff + m * 2048 + k * 1024); } while (0)
; #define PG8_MMA(ai, bj, At, Bt) do { __builtin_amdgcn_s_setprio(1); _Pragma("unroll") for (int m = 0; m < 4; ++m) _Pragma("unroll") for (int n = 0; n < 2; ++n) _Pragma("unroll") for (int k = 0; k < 2; ++k) \
;         acc[ai][bj][m][n] = __builtin_amdgcn_mfma_f32_16x16x32_bf16(Bt[n][k], At[m][k], acc[ai][bj][m][n], 0, 0, 0); __builtin_amdgcn_s_setprio(0); } while (0)
; #define PG8_WAIT_V(n) asm volatile("s_waitcnt vmcnt(" #n ")" ::: "memory")
; #define PG8_WAIT_L(n) asm volatile("s_waitcnt lgkmcnt(" #n ")" ::: "memory")
; #define PG8_BAR __builtin_amdgcn_s_barrier()
; #define PG8_SCHED __builtin_amdgcn_sched_barrier(0)
; template <class Epi, class Sched, bool ALIGN_EPI = false, bool SP2 = false>
; __device__ __forceinline__ void gemm_phase(PG8_LAS unsigned char* lds, const Gemm g, const Sched& S, const Epi& E, int wave_in) {
;     ...
;             PG8_LDA(At, 1, 1); PG8_STAGE(PG8_SB(1, 0), b3, voffB); PG8_STAGE(PG8_SB(1, 1), b3 + hstep, voffB); PG8_STAGE(PG8_SA(1, 0), a3, voffA);
;             PG8_WAIT_V(8); PG8_WAIT_L(0); PG8_BAR; PG8_MMA(1, 0, At, B0); PG8_MMA(1, 1, At, B1); PG8_BAR; PG8_SCHED;
;     ...
;         if constexpr (ALIGN_EPI) { if (wr == 0) PG8_BAR; }
;         if constexpr (!Epi::AFTER_DRAIN) { E(acc, cur, wr, wc, fr, fq); S.done(cur); }
;         if (!has_next) break;
	s_add_i32 s26, s47, s30
	v_lshl_add_u64 v[144:145], v[144:145], 0, s[84:85]
	s_mov_b32 m0, s26
	ds_read_b128 v[188:191], v149 offset:49152
	ds_read_b128 v[212:215], v149 offset:50176
	ds_read_b128 v[216:219], v149 offset:51200
	ds_read_b128 v[220:223], v149 offset:52224
	ds_read_b128 v[224:227], v149 offset:53248
	ds_read_b128 v[228:231], v149 offset:54272
	ds_read_b128 v[232:235], v149 offset:55296
	ds_read_b128 v[236:239], v149 offset:56320
	global_load_lds_dwordx4 v[144:145], off
	s_add_i32 m0, s26, 0x2000
	s_add_u32 s24, s24, 0x40080
	v_lshl_add_u64 v[144:145], v[192:193], 0, s[84:85]
	s_addc_u32 s25, s25, 0
	s_add_i32 s26, s48, s30
	global_load_lds_dwordx4 v[144:145], off
	v_lshl_add_u64 v[144:145], s[24:25], 0, v[0:1]
	s_mov_b32 m0, s26
	s_nop 0
	global_load_lds_dwordx4 v[144:145], off
	v_lshl_add_u64 v[144:145], s[24:25], 0, v[130:131]
	s_add_i32 m0, s26, 0x2000
	s_nop 0
	global_load_lds_dwordx4 v[144:145], off
	v_lshl_add_u64 v[144:145], v[240:241], 0, s[84:85]
	s_mov_b32 m0, s37
	s_nop 0
	global_load_lds_dwordx4 v[144:145], off
	v_lshl_add_u64 v[144:145], v[242:243], 0, s[84:85]
	s_mov_b32 m0, s38
	s_nop 0
	global_load_lds_dwordx4 v[144:145], off
	s_waitcnt vmcnt(8) lgkmcnt(0)
	s_barrier
	v_mfma_f32_16x16x32_bf16 v[62:65], v[140:143], v[188:191], v[62:65]
	v_mfma_f32_16x16x32_bf16 v[58:61], v[154:157], v[188:191], v[58:61]
	v_mfma_f32_16x16x32_bf16 v[54:57], v[140:143], v[216:219], v[54:57]
	v_mfma_f32_16x16x32_bf16 v[42:45], v[154:157], v[216:219], v[42:45]
	v_mfma_f32_16x16x32_bf16 v[38:41], v[140:143], v[224:227], v[38:41]
	v_mfma_f32_16x16x32_bf16 v[26:29], v[154:157], v[224:227], v[26:29]
	v_mfma_f32_16x16x32_bf16 v[22:25], v[140:143], v[232:235], v[22:25]
	v_mfma_f32_16x16x32_bf16 v[10:13], v[154:157], v[232:235], v[10:13]
	v_mfma_f32_16x16x32_bf16 v[62:65], v[150:153], v[212:215], v[62:65]
	v_mfma_f32_16x16x32_bf16 v[58:61], v[168:171], v[212:215], v[58:61]
	v_mfma_f32_16x16x32_bf16 v[54:57], v[150:153], v[220:223], v[54:57]
	v_mfma_f32_16x16x32_bf16 v[42:45], v[168:171], v[220:223], v[42:45]
	v_mfma_f32_16x16x32_bf16 v[38:41], v[150:153], v[228:231], v[38:41]
	v_mfma_f32_16x16x32_bf16 v[26:29], v[168:171], v[228:231], v[26:29]
	v_mfma_f32_16x16x32_bf16 v[22:25], v[150:153], v[236:239], v[22:25]
	v_mfma_f32_16x16x32_bf16 v[10:13], v[168:171], v[236:239], v[10:13]
	v_mfma_f32_16x16x32_bf16 v[50:53], v[172:175], v[188:191], v[50:53]
	v_mfma_f32_16x16x32_bf16 v[46:49], v[180:183], v[188:191], v[46:49]
	v_mfma_f32_16x16x32_bf16 v[34:37], v[172:175], v[216:219], v[34:37]
	v_mfma_f32_16x16x32_bf16 v[30:33], v[180:183], v[216:219], v[30:33]
	v_mfma_f32_16x16x32_bf16 v[18:21], v[172:175], v[224:227], v[18:21]
	v_mfma_f32_16x16x32_bf16 v[14:17], v[180:183], v[224:227], v[14:17]
	v_mfma_f32_16x16x32_bf16 v[6:9], v[172:175], v[232:235], v[6:9]
	v_mfma_f32_16x16x32_bf16 v[2:5], v[180:183], v[232:235], v[2:5]
	v_mfma_f32_16x16x32_bf16 v[50:53], v[176:179], v[212:215], v[50:53]
	v_mfma_f32_16x16x32_bf16 v[46:49], v[184:187], v[212:215], v[46:49]
	v_mfma_f32_16x16x32_bf16 v[34:37], v[176:179], v[220:223], v[34:37]
	v_mfma_f32_16x16x32_bf16 v[30:33], v[184:187], v[220:223], v[30:33]
	v_mfma_f32_16x16x32_bf16 v[18:21], v[176:179], v[228:231], v[18:21]
	v_mfma_f32_16x16x32_bf16 v[14:17], v[184:187], v[228:231], v[14:17]
	v_mfma_f32_16x16x32_bf16 v[6:9], v[176:179], v[236:239], v[6:9]
	v_mfma_f32_16x16x32_bf16 v[2:5], v[184:187], v[236:239], v[2:5]
	s_barrier
	s_add_i32 s46, s46, 2
	s_add_u32 s22, s22, 0x100
	s_addc_u32 s23, s23, 0
	s_add_u32 s44, s44, 0x100
	s_addc_u32 s45, s45, 0
	s_cmp_gt_u32 s46, 13
	s_cbranch_scc0 .LBB0_84
	s_and_b64 vcc, exec, s[8:9]
	v_readlane_b32 s26, v254, 6
	v_readlane_b32 s27, v254, 7
	s_cbranch_vccz .LBB0_87
	s_barrier

; #define PG8_STAGE(bufoff, gbase, voff) do { _Pragma("unroll") for (int _i = 0; _i < 2; ++_i) \
;         __builtin_amdgcn_global_load_lds((const unsigned*)((const char*)(gbase) + (voff)[_i]), (PG8_LAS unsigned*)(lds + (bufoff) + ldsw + _i * 8192), 16, 0, 0); } while (0)
; #define PG8_LDA(dst, b, h) do { _Pragma("unroll") for (int m = 0; m < 4; ++m) _Pragma("unroll") for (int k = 0; k < 2; ++k) dst[m][k] = *(const PG8_LAS bf16x8*)(lds + PG8_SA(b, h) + aoff + m * 2048 + k * 1024); } while (0)
; #define PG8_LDB(dst, b, h) do { _Pragma("unroll") for (int n = 0; n < 2; ++n) _Pragma("unroll") for (int k = 0; k < 2; ++k) dst[n][k] = *(const PG8_LAS bf16x8*)(lds + PG8_SB(b, h) + boff + n * 2048 + k * 1024); } while (0)
; #define PG8_MMA(ai, bj, At, Bt) do { __builtin_amdgcn_s_setprio(1); _Pragma("unroll") for (int m = 0; m < 4; ++m) _Pragma("unroll") for (int n = 0; n < 2; ++n) _Pragma("unroll") for (int k = 0; k < 2; ++k) \
;         acc[ai][bj][m][n] = __builtin_amdgcn_mfma_f32_16x16x32_bf16(Bt[n][k], At[m][k], acc[ai][bj][m][n], 0, 0, 0); __builtin_amdgcn_s_setprio(0); } while (0)
; #define PG8_WAIT_V(n) asm volatile("s_waitcnt vmcnt(" #n ")" ::: "memory")
; #define PG8_WAIT_L(n) asm volatile("s_waitcnt lgkmcnt(" #n ")" ::: "memory")
; template <class Epi, class Sched, bool ALIGN_EPI = false, bool SP2 = false>
; __device__ __forceinline__ void gemm_phase(PG8_LAS unsigned char* lds, const Gemm g, const Sched& S, const Epi& E, int wave_in) {
;     ...
;             const bool last = (t == nt - 2);
;             const char* a1 = cA + (size_t)(t + 1) * kstep;
;             const char* a2 = last ? nA : cA + (size_t)(t + 2) * kstep; const char* b2 = last ? nB : cB + (size_t)(t + 2) * kstep;
;             const char* a3 = a2 + kstep; const char* b3 = b2 + kstep;
;             if (last && has_next) S.a_ready(nxt);
;             if constexpr (SP2) {
;             PG8_LDB(B0, 0, 0); PG8_LDB(B1, 0, 1); PG8_SCHED; PG8_LDA(At, 0, 0); PG8_STAGE(PG8_SA(1, 1), a1 + hstepA, voffA);
;             PG8_WAIT_V(8); PG8_WAIT_L(0); PG8_BAR; PG8_MMA(0, 0, At, B0); PG8_MMA(0, 1, At, B1); PG8_BAR; PG8_SCHED;
;             PG8_LDA(At, 0, 1); PG8_STAGE(PG8_SB(0, 0), b2, voffB); PG8_STAGE(PG8_SB(0, 1), b2 + hstep, voffB); PG8_STAGE(PG8_SA(0, 0), a2, voffA);
;             PG8_WAIT_V(8); PG8_WAIT_L(0); PG8_BAR; PG8_MMA(1, 0, At, B0); PG8_MMA(1, 1, At, B1); PG8_BAR; PG8_SCHED;
.LBB0_107:
	s_add_u32 s28, s26, 0xfff80080
	s_addc_u32 s29, s27, -1
	s_add_i32 s55, 0, 0x10000
	s_cmp_eq_u32 s54, 4
	s_cselect_b32 s31, s21, s29
	s_cselect_b32 s30, s50, s28
	v_add_u32_e32 v144, s55, v147
	s_cselect_b32 s29, s19, s53
	s_cselect_b32 s28, s51, s52
	s_add_i32 s58, 0, 0x14000
	ds_read_b128 v[140:143], v144
	ds_read_b128 v[150:153], v144 offset:1024
	ds_read_b128 v[154:157], v144 offset:2048
	ds_read_b128 v[168:171], v144 offset:3072
	v_add_u32_e32 v144, s58, v147
	ds_read_b128 v[172:175], v144
	ds_read_b128 v[176:179], v144 offset:1024
	ds_read_b128 v[180:183], v144 offset:2048
	ds_read_b128 v[184:187], v144 offset:3072
	v_lshl_add_u64 v[144:145], s[26:27], 0, v[136:137]
	s_add_i32 m0, s41, 0xc000
	ds_read_b128 v[188:191], v149
	ds_read_b128 v[212:215], v149 offset:1024
	ds_read_b128 v[216:219], v149 offset:2048
	ds_read_b128 v[220:223], v149 offset:3072
	ds_read_b128 v[224:227], v149 offset:4096
	ds_read_b128 v[228:231], v149 offset:5120
	ds_read_b128 v[232:235], v149 offset:6144
	ds_read_b128 v[236:239], v149 offset:7168
	global_load_lds_dwordx4 v[144:145], off
	v_lshl_add_u64 v[144:145], s[26:27], 0, v[138:139]
	s_add_i32 m0, s41, 0xe000
	s_nop 0
	global_load_lds_dwordx4 v[144:145], off
	s_waitcnt vmcnt(8) lgkmcnt(0)
	s_barrier
	v_mfma_f32_16x16x32_bf16 v[126:129], v[140:143], v[188:191], v[126:129]
	v_mfma_f32_16x16x32_bf16 v[122:125], v[154:157], v[188:191], v[122:125]
	v_mfma_f32_16x16x32_bf16 v[110:113], v[140:143], v[216:219], v[110:113]
	v_mfma_f32_16x16x32_bf16 v[106:109], v[154:157], v[216:219], v[106:109]
	v_mfma_f32_16x16x32_bf16 v[94:97], v[140:143], v[224:227], v[94:97]
	v_mfma_f32_16x16x32_bf16 v[90:93], v[154:157], v[224:227], v[90:93]
	v_mfma_f32_16x16x32_bf16 v[78:81], v[140:143], v[232:235], v[78:81]
	v_mfma_f32_16x16x32_bf16 v[74:77], v[154:157], v[232:235], v[74:77]
	v_mfma_f32_16x16x32_bf16 v[126:129], v[150:153], v[212:215], v[126:129]
	v_mfma_f32_16x16x32_bf16 v[122:125], v[168:171], v[212:215], v[122:125]
	v_mfma_f32_16x16x32_bf16 v[110:113], v[150:153], v[220:223], v[110:113]
	v_mfma_f32_16x16x32_bf16 v[106:109], v[168:171], v[220:223], v[106:109]
	v_mfma_f32_16x16x32_bf16 v[94:97], v[150:153], v[228:231], v[94:97]
	v_mfma_f32_16x16x32_bf16 v[90:93], v[168:171], v[228:231], v[90:93]
	v_mfma_f32_16x16x32_bf16 v[78:81], v[150:153], v[236:239], v[78:81]
	v_mfma_f32_16x16x32_bf16 v[74:77], v[168:171], v[236:239], v[74:77]
	v_mfma_f32_16x16x32_bf16 v[118:121], v[172:175], v[188:191], v[118:121]
	v_mfma_f32_16x16x32_bf16 v[114:117], v[180:183], v[188:191], v[114:117]
	v_mfma_f32_16x16x32_bf16 v[102:105], v[172:175], v[216:219], v[102:105]
	v_mfma_f32_16x16x32_bf16 v[98:101], v[180:183], v[216:219], v[98:101]
	v_mfma_f32_16x16x32_bf16 v[86:89], v[172:175], v[224:227], v[86:89]
	v_mfma_f32_16x16x32_bf16 v[82:85], v[180:183], v[224:227], v[82:85]
	v_mfma_f32_16x16x32_bf16 v[70:73], v[172:175], v[232:235], v[70:73]
	v_mfma_f32_16x16x32_bf16 v[66:69], v[180:183], v[232:235], v[66:69]
	v_mfma_f32_16x16x32_bf16 v[118:121], v[176:179], v[212:215], v[118:121]
	v_mfma_f32_16x16x32_bf16 v[114:117], v[184:187], v[212:215], v[114:117]
	v_mfma_f32_16x16x32_bf16 v[102:105], v[176:179], v[220:223], v[102:105]
	v_mfma_f32_16x16x32_bf16 v[98:101], v[184:187], v[220:223], v[98:101]
	v_mfma_f32_16x16x32_bf16 v[86:89], v[176:179], v[228:231], v[86:89]
	v_mfma_f32_16x16x32_bf16 v[82:85], v[184:187], v[228:231], v[82:85]
	v_mfma_f32_16x16x32_bf16 v[70:73], v[176:179], v[236:239], v[70:73]
	v_mfma_f32_16x16x32_bf16 v[66:69], v[184:187], v[236:239], v[66:69]
	s_barrier
	s_add_i32 s55, s55, s40
	v_lshl_add_u64 v[144:145], s[28:29], 0, v[0:1]
	s_mov_b32 m0, s55
	ds_read_b128 v[188:191], v149 offset:16384
	ds_read_b128 v[212:215], v149 offset:17408
	ds_read_b128 v[216:219], v149 offset:18432
	ds_read_b128 v[220:223], v149 offset:19456
	ds_read_b128 v[224:227], v149 offset:20480
	ds_read_b128 v[228:231], v149 offset:21504
	ds_read_b128 v[232:235], v149 offset:22528
	ds_read_b128 v[236:239], v149 offset:23552
	global_load_lds_dwordx4 v[144:145], off
	s_add_i32 m0, s55, 0x2000
	s_add_u32 s56, s28, 0x20000
	v_lshl_add_u64 v[192:193], s[28:29], 0, v[130:131]
	s_addc_u32 s57, s29, 0
	s_add_i32 s55, s58, s40
	global_load_lds_dwordx4 v[192:193], off
	v_lshl_add_u64 v[240:241], s[56:57], 0, v[0:1]
	s_mov_b32 m0, s55
	v_lshl_add_u64 v[242:243], s[30:31], 0, v[132:133]
	global_load_lds_dwordx4 v[240:241], off
	v_lshl_add_u64 v[240:241], s[56:57], 0, v[130:131]
	s_add_i32 m0, s55, 0x2000
	s_nop 0
	global_load_lds_dwordx4 v[240:241], off
	v_lshl_add_u64 v[240:241], s[30:31], 0, v[134:135]
	s_mov_b32 m0, s41
	s_nop 0
	global_load_lds_dwordx4 v[240:241], off
	s_mov_b32 m0, s42
	s_nop 0
	global_load_lds_dwordx4 v[242:243], off
	s_waitcnt vmcnt(8) lgkmcnt(0)
	s_barrier
; #define PG8_STAGE(bufoff, gbase, voff) do { _Pragma("unroll") for (int _i = 0; _i < 2; ++_i) \
;         __builtin_amdgcn_global_load_lds((const unsigned*)((const char*)(gbase) + (voff)[_i]), (PG8_LAS unsigned*)(lds + (bufoff) + ldsw + _i * 8192), 16, 0, 0); } while (0)
; #define PG8_LDA(dst, b, h) do { _Pragma("unroll") for (int m = 0; m < 4; ++m) _Pragma("unroll") for (int k = 0; k < 2; ++k) dst[m][k] = *(const PG8_LAS bf16x8*)(lds + PG8_SA(b, h) + aoff + m * 2048 + k * 1024); } while (0)
; #define PG8_LDB(dst, b, h) do { _Pragma("unroll") for (int n = 0; n < 2; ++n) _Pragma("unroll") for (int k = 0; k < 2; ++k) dst[n][k] = *(const PG8_LAS bf16x8*)(lds + PG8_SB(b, h) + boff + n * 2048 + k * 1024); } while (0)
; #define PG8_MMA(ai, bj, At, Bt) do { __builtin_amdgcn_s_setprio(1); _Pragma("unroll") for (int m = 0; m < 4; ++m) _Pragma("unroll") for (int n = 0; n < 2; ++n) _Pragma("unroll") for (int k = 0; k < 2; ++k) \
;         acc[ai][bj][m][n] = __builtin_amdgcn_mfma_f32_16x16x32_bf16(Bt[n][k], At[m][k], acc[ai][bj][m][n], 0, 0, 0); __builtin_amdgcn_s_setprio(0); } while (0)
; #define PG8_WAIT_V(n) asm volatile("s_waitcnt vmcnt(" #n ")" ::: "memory")
; #define PG8_WAIT_L(n) asm volatile("s_waitcnt lgkmcnt(" #n ")" ::: "memory")
; #define PG8_BAR __builtin_amdgcn_s_barrier()
; #define PG8_SCHED __builtin_amdgcn_sched_barrier(0)
; template <class Epi, class Sched, bool ALIGN_EPI = false, bool SP2 = false>
; __device__ __forceinline__ void gemm_phase(PG8_LAS unsigned char* lds, const Gemm g, const Sched& S, const Epi& E, int wave_in) {
;     ...
;             PG8_WAIT_V(8); PG8_WAIT_L(0); PG8_BAR; PG8_MMA(1, 0, At, B0); PG8_MMA(1, 1, At, B1); PG8_BAR; PG8_SCHED;
;             PG8_LDB(B0, 1, 0); PG8_LDB(B1, 1, 1); PG8_SCHED; PG8_LDA(At, 1, 0); PG8_STAGE(PG8_SA(0, 1), a2 + hstepA, voffA);
;             PG8_WAIT_V(8); PG8_WAIT_L(0); PG8_BAR; PG8_MMA(0, 0, At, B0); PG8_MMA(0, 1, At, B1); PG8_BAR; PG8_SCHED;
	v_mfma_f32_16x16x32_bf16 v[62:65], v[140:143], v[188:191], v[62:65]
	v_mfma_f32_16x16x32_bf16 v[58:61], v[154:157], v[188:191], v[58:61]
	v_mfma_f32_16x16x32_bf16 v[46:49], v[140:143], v[216:219], v[46:49]
	v_mfma_f32_16x16x32_bf16 v[42:45], v[154:157], v[216:219], v[42:45]
	v_mfma_f32_16x16x32_bf16 v[30:33], v[140:143], v[224:227], v[30:33]
	v_mfma_f32_16x16x32_bf16 v[26:29], v[154:157], v[224:227], v[26:29]
	v_mfma_f32_16x16x32_bf16 v[14:17], v[140:143], v[232:235], v[14:17]
	v_mfma_f32_16x16x32_bf16 v[10:13], v[154:157], v[232:235], v[10:13]
	v_mfma_f32_16x16x32_bf16 v[62:65], v[150:153], v[212:215], v[62:65]
	v_mfma_f32_16x16x32_bf16 v[58:61], v[168:171], v[212:215], v[58:61]
	v_mfma_f32_16x16x32_bf16 v[46:49], v[150:153], v[220:223], v[46:49]
	v_mfma_f32_16x16x32_bf16 v[42:45], v[168:171], v[220:223], v[42:45]
	v_mfma_f32_16x16x32_bf16 v[30:33], v[150:153], v[228:231], v[30:33]
	v_mfma_f32_16x16x32_bf16 v[26:29], v[168:171], v[228:231], v[26:29]
	v_mfma_f32_16x16x32_bf16 v[14:17], v[150:153], v[236:239], v[14:17]
	v_mfma_f32_16x16x32_bf16 v[10:13], v[168:171], v[236:239], v[10:13]
	v_mfma_f32_16x16x32_bf16 v[54:57], v[172:175], v[188:191], v[54:57]
	v_mfma_f32_16x16x32_bf16 v[50:53], v[180:183], v[188:191], v[50:53]
	v_mfma_f32_16x16x32_bf16 v[38:41], v[172:175], v[216:219], v[38:41]
	v_mfma_f32_16x16x32_bf16 v[34:37], v[180:183], v[216:219], v[34:37]
	v_mfma_f32_16x16x32_bf16 v[22:25], v[172:175], v[224:227], v[22:25]
	v_mfma_f32_16x16x32_bf16 v[18:21], v[180:183], v[224:227], v[18:21]
	v_mfma_f32_16x16x32_bf16 v[6:9], v[172:175], v[232:235], v[6:9]
	v_mfma_f32_16x16x32_bf16 v[2:5], v[180:183], v[232:235], v[2:5]
	v_mfma_f32_16x16x32_bf16 v[54:57], v[176:179], v[212:215], v[54:57]
	v_mfma_f32_16x16x32_bf16 v[50:53], v[184:187], v[212:215], v[50:53]
	v_mfma_f32_16x16x32_bf16 v[38:41], v[176:179], v[220:223], v[38:41]
	v_mfma_f32_16x16x32_bf16 v[34:37], v[184:187], v[220:223], v[34:37]
	v_mfma_f32_16x16x32_bf16 v[22:25], v[176:179], v[228:231], v[22:25]
	v_mfma_f32_16x16x32_bf16 v[18:21], v[184:187], v[228:231], v[18:21]
	v_mfma_f32_16x16x32_bf16 v[6:9], v[176:179], v[236:239], v[6:9]
	v_mfma_f32_16x16x32_bf16 v[2:5], v[184:187], v[236:239], v[2:5]
	s_barrier
	s_add_i32 s55, 0, 0x18000
	s_add_i32 s56, 0, 0x1c000
	v_add_u32_e32 v168, s55, v147
	v_add_u32_e32 v184, s56, v147
	ds_read_b128 v[140:143], v168
	ds_read_b128 v[150:153], v168 offset:1024
	ds_read_b128 v[154:157], v168 offset:2048
	ds_read_b128 v[168:171], v168 offset:3072
	ds_read_b128 v[172:175], v184
	ds_read_b128 v[176:179], v184 offset:1024
	ds_read_b128 v[180:183], v184 offset:2048
	ds_read_b128 v[184:187], v184 offset:3072
	s_add_u32 s30, s30, 0x80000
	s_addc_u32 s31, s31, 0
	s_mov_b32 m0, s43
	v_lshl_add_u64 v[244:245], s[30:31], 0, v[134:135]
	ds_read_b128 v[188:191], v149 offset:32768
	ds_read_b128 v[212:215], v149 offset:33792
	ds_read_b128 v[216:219], v149 offset:34816
	ds_read_b128 v[220:223], v149 offset:35840
	ds_read_b128 v[224:227], v149 offset:36864
	ds_read_b128 v[228:231], v149 offset:37888
	ds_read_b128 v[232:235], v149 offset:38912
	ds_read_b128 v[236:239], v149 offset:39936
	global_load_lds_dwordx4 v[244:245], off
	v_lshl_add_u64 v[244:245], s[30:31], 0, v[132:133]
	s_mov_b32 m0, s44
	s_nop 0
	global_load_lds_dwordx4 v[244:245], off
	s_waitcnt vmcnt(8) lgkmcnt(0)
	s_barrier
	v_mfma_f32_16x16x32_bf16 v[126:129], v[140:143], v[188:191], v[126:129]
	v_mfma_f32_16x16x32_bf16 v[122:125], v[154:157], v[188:191], v[122:125]
	v_mfma_f32_16x16x32_bf16 v[110:113], v[140:143], v[216:219], v[110:113]
	v_mfma_f32_16x16x32_bf16 v[106:109], v[154:157], v[216:219], v[106:109]
	v_mfma_f32_16x16x32_bf16 v[94:97], v[140:143], v[224:227], v[94:97]
	v_mfma_f32_16x16x32_bf16 v[90:93], v[154:157], v[224:227], v[90:93]
	v_mfma_f32_16x16x32_bf16 v[78:81], v[140:143], v[232:235], v[78:81]
	v_mfma_f32_16x16x32_bf16 v[74:77], v[154:157], v[232:235], v[74:77]
	v_mfma_f32_16x16x32_bf16 v[126:129], v[150:153], v[212:215], v[126:129]
	v_mfma_f32_16x16x32_bf16 v[122:125], v[168:171], v[212:215], v[122:125]
	v_mfma_f32_16x16x32_bf16 v[110:113], v[150:153], v[220:223], v[110:113]
	v_mfma_f32_16x16x32_bf16 v[106:109], v[168:171], v[220:223], v[106:109]
	v_mfma_f32_16x16x32_bf16 v[94:97], v[150:153], v[228:231], v[94:97]
	v_mfma_f32_16x16x32_bf16 v[90:93], v[168:171], v[228:231], v[90:93]
	v_mfma_f32_16x16x32_bf16 v[78:81], v[150:153], v[236:239], v[78:81]
	v_mfma_f32_16x16x32_bf16 v[74:77], v[168:171], v[236:239], v[74:77]
	v_mfma_f32_16x16x32_bf16 v[118:121], v[172:175], v[188:191], v[118:121]
	v_mfma_f32_16x16x32_bf16 v[114:117], v[180:183], v[188:191], v[114:117]
	v_mfma_f32_16x16x32_bf16 v[102:105], v[172:175], v[216:219], v[102:105]
	v_mfma_f32_16x16x32_bf16 v[98:101], v[180:183], v[216:219], v[98:101]
	v_mfma_f32_16x16x32_bf16 v[86:89], v[172:175], v[224:227], v[86:89]
	v_mfma_f32_16x16x32_bf16 v[82:85], v[180:183], v[224:227], v[82:85]
	v_mfma_f32_16x16x32_bf16 v[70:73], v[172:175], v[232:235], v[70:73]
	v_mfma_f32_16x16x32_bf16 v[66:69], v[180:183], v[232:235], v[66:69]
	v_mfma_f32_16x16x32_bf16 v[118:121], v[176:179], v[212:215], v[118:121]
	v_mfma_f32_16x16x32_bf16 v[114:117], v[184:187], v[212:215], v[114:117]
	v_mfma_f32_16x16x32_bf16 v[102:105], v[176:179], v[220:223], v[102:105]
	v_mfma_f32_16x16x32_bf16 v[98:101], v[184:187], v[220:223], v[98:101]
	v_mfma_f32_16x16x32_bf16 v[86:89], v[176:179], v[228:231], v[86:89]
	v_mfma_f32_16x16x32_bf16 v[82:85], v[184:187], v[228:231], v[82:85]
	v_mfma_f32_16x16x32_bf16 v[70:73], v[176:179], v[236:239], v[70:73]
	v_mfma_f32_16x16x32_bf16 v[66:69], v[184:187], v[236:239], v[66:69]
	s_barrier
; #define PG8_STAGE(bufoff, gbase, voff) do { _Pragma("unroll") for (int _i = 0; _i < 2; ++_i) \
;         __builtin_amdgcn_global_load_lds((const unsigned*)((const char*)(gbase) + (voff)[_i]), (PG8_LAS unsigned*)(lds + (bufoff) + ldsw + _i * 8192), 16, 0, 0); } while (0)
; #define PG8_LDA(dst, b, h) do { _Pragma("unroll") for (int m = 0; m < 4; ++m) _Pragma("unroll") for (int k = 0; k < 2; ++k) dst[m][k] = *(const PG8_LAS bf16x8*)(lds + PG8_SA(b, h) + aoff + m * 2048 + k * 1024); } while (0)
; #define PG8_MMA(ai, bj, At, Bt) do { __builtin_amdgcn_s_setprio(1); _Pragma("unroll") for (int m = 0; m < 4; ++m) _Pragma("unroll") for (int n = 0; n < 2; ++n) _Pragma("unroll") for (int k = 0; k < 2; ++k) \
;         acc[ai][bj][m][n] = __builtin_amdgcn_mfma_f32_16x16x32_bf16(Bt[n][k], At[m][k], acc[ai][bj][m][n], 0, 0, 0); __builtin_amdgcn_s_setprio(0); } while (0)
; #define PG8_WAIT_V(n) asm volatile("s_waitcnt vmcnt(" #n ")" ::: "memory")
; #define PG8_WAIT_L(n) asm volatile("s_waitcnt lgkmcnt(" #n ")" ::: "memory")
; #define PG8_BAR __builtin_amdgcn_s_barrier()
; #define PG8_SCHED __builtin_amdgcn_sched_barrier(0)
; template <class Epi, class Sched, bool ALIGN_EPI = false, bool SP2 = false>
; __device__ __forceinline__ void gemm_phase(PG8_LAS unsigned char* lds, const Gemm g, const Sched& S, const Epi& E, int wave_in) {
;     ...
;             PG8_LDA(At, 1, 1); PG8_STAGE(PG8_SB(1, 0), b3, voffB); PG8_STAGE(PG8_SB(1, 1), b3 + hstep, voffB); PG8_STAGE(PG8_SA(1, 0), a3, voffA);
;             PG8_WAIT_V(8); PG8_WAIT_L(0); PG8_BAR; PG8_MMA(1, 0, At, B0); PG8_MMA(1, 1, At, B1); PG8_BAR; PG8_SCHED;
;     ...
;         if constexpr (ALIGN_EPI) { if (wr == 0) PG8_BAR; }
;         if constexpr (!Epi::AFTER_DRAIN) { E(acc, cur, wr, wc, fr, fq); S.done(cur); }
;         if (!has_next) break;
	s_add_i32 s30, s55, s40
	v_lshl_add_u64 v[144:145], v[144:145], 0, s[84:85]
	s_mov_b32 m0, s30
	ds_read_b128 v[188:191], v149 offset:49152
	ds_read_b128 v[212:215], v149 offset:50176
	ds_read_b128 v[216:219], v149 offset:51200
	ds_read_b128 v[220:223], v149 offset:52224
	ds_read_b128 v[224:227], v149 offset:53248
	ds_read_b128 v[228:231], v149 offset:54272
	ds_read_b128 v[232:235], v149 offset:55296
	ds_read_b128 v[236:239], v149 offset:56320
	global_load_lds_dwordx4 v[144:145], off
	s_add_i32 m0, s30, 0x2000
	s_add_u32 s28, s28, 0x20080
	v_lshl_add_u64 v[144:145], v[192:193], 0, s[84:85]
	s_addc_u32 s29, s29, 0
	s_add_i32 s30, s56, s40
	global_load_lds_dwordx4 v[144:145], off
	v_lshl_add_u64 v[144:145], s[28:29], 0, v[0:1]
	s_mov_b32 m0, s30
	s_nop 0
	global_load_lds_dwordx4 v[144:145], off
	v_lshl_add_u64 v[144:145], s[28:29], 0, v[130:131]
	s_add_i32 m0, s30, 0x2000
	s_nop 0
	global_load_lds_dwordx4 v[144:145], off
	v_lshl_add_u64 v[144:145], v[240:241], 0, s[84:85]
	s_mov_b32 m0, s45
	s_nop 0
	global_load_lds_dwordx4 v[144:145], off
	v_lshl_add_u64 v[144:145], v[242:243], 0, s[84:85]
	s_mov_b32 m0, s46
	s_nop 0
	global_load_lds_dwordx4 v[144:145], off
	s_waitcnt vmcnt(8) lgkmcnt(0)
	s_barrier
	v_mfma_f32_16x16x32_bf16 v[62:65], v[140:143], v[188:191], v[62:65]
	v_mfma_f32_16x16x32_bf16 v[58:61], v[154:157], v[188:191], v[58:61]
	v_mfma_f32_16x16x32_bf16 v[46:49], v[140:143], v[216:219], v[46:49]
	v_mfma_f32_16x16x32_bf16 v[42:45], v[154:157], v[216:219], v[42:45]
	v_mfma_f32_16x16x32_bf16 v[30:33], v[140:143], v[224:227], v[30:33]
	v_mfma_f32_16x16x32_bf16 v[26:29], v[154:157], v[224:227], v[26:29]
	v_mfma_f32_16x16x32_bf16 v[14:17], v[140:143], v[232:235], v[14:17]
	v_mfma_f32_16x16x32_bf16 v[10:13], v[154:157], v[232:235], v[10:13]
	v_mfma_f32_16x16x32_bf16 v[62:65], v[150:153], v[212:215], v[62:65]
	v_mfma_f32_16x16x32_bf16 v[58:61], v[168:171], v[212:215], v[58:61]
	v_mfma_f32_16x16x32_bf16 v[46:49], v[150:153], v[220:223], v[46:49]
	v_mfma_f32_16x16x32_bf16 v[42:45], v[168:171], v[220:223], v[42:45]
	v_mfma_f32_16x16x32_bf16 v[30:33], v[150:153], v[228:231], v[30:33]
	v_mfma_f32_16x16x32_bf16 v[26:29], v[168:171], v[228:231], v[26:29]
	v_mfma_f32_16x16x32_bf16 v[14:17], v[150:153], v[236:239], v[14:17]
	v_mfma_f32_16x16x32_bf16 v[10:13], v[168:171], v[236:239], v[10:13]
	v_mfma_f32_16x16x32_bf16 v[54:57], v[172:175], v[188:191], v[54:57]
	v_mfma_f32_16x16x32_bf16 v[50:53], v[180:183], v[188:191], v[50:53]
	v_mfma_f32_16x16x32_bf16 v[38:41], v[172:175], v[216:219], v[38:41]
	v_mfma_f32_16x16x32_bf16 v[34:37], v[180:183], v[216:219], v[34:37]
	v_mfma_f32_16x16x32_bf16 v[22:25], v[172:175], v[224:227], v[22:25]
	v_mfma_f32_16x16x32_bf16 v[18:21], v[180:183], v[224:227], v[18:21]
	v_mfma_f32_16x16x32_bf16 v[6:9], v[172:175], v[232:235], v[6:9]
	v_mfma_f32_16x16x32_bf16 v[2:5], v[180:183], v[232:235], v[2:5]
	v_mfma_f32_16x16x32_bf16 v[54:57], v[176:179], v[212:215], v[54:57]
	v_mfma_f32_16x16x32_bf16 v[50:53], v[184:187], v[212:215], v[50:53]
	v_mfma_f32_16x16x32_bf16 v[38:41], v[176:179], v[220:223], v[38:41]
	v_mfma_f32_16x16x32_bf16 v[34:37], v[184:187], v[220:223], v[34:37]
	v_mfma_f32_16x16x32_bf16 v[22:25], v[176:179], v[228:231], v[22:25]
	v_mfma_f32_16x16x32_bf16 v[18:21], v[184:187], v[228:231], v[18:21]
	v_mfma_f32_16x16x32_bf16 v[6:9], v[176:179], v[236:239], v[6:9]
	v_mfma_f32_16x16x32_bf16 v[2:5], v[184:187], v[236:239], v[2:5]
	s_barrier
	s_add_i32 s54, s54, 2
	s_add_u32 s26, s26, 0x100
	s_addc_u32 s27, s27, 0
	s_add_u32 s52, s52, 0x100
	s_addc_u32 s53, s53, 0
	s_cmp_gt_u32 s54, 5
	s_cbranch_scc0 .LBB0_107
	s_and_b64 vcc, exec, s[16:17]
	s_cbranch_vccz .LBB0_110
	s_barrier

; #define PG8_STAGE(bufoff, gbase, voff) do { _Pragma("unroll") for (int _i = 0; _i < 2; ++_i) \
;         __builtin_amdgcn_global_load_lds((const unsigned*)((const char*)(gbase) + (voff)[_i]), (PG8_LAS unsigned*)(lds + (bufoff) + ldsw + _i * 8192), 16, 0, 0); } while (0)
; #define PG8_LDA(dst, b, h) do { _Pragma("unroll") for (int m = 0; m < 4; ++m) _Pragma("unroll") for (int k = 0; k < 2; ++k) dst[m][k] = *(const PG8_LAS bf16x8*)(lds + PG8_SA(b, h) + aoff + m * 2048 + k * 1024); } while (0)
; #define PG8_LDB(dst, b, h) do { _Pragma("unroll") for (int n = 0; n < 2; ++n) _Pragma("unroll") for (int k = 0; k < 2; ++k) dst[n][k] = *(const PG8_LAS bf16x8*)(lds + PG8_SB(b, h) + boff + n * 2048 + k * 1024); } while (0)
; #define PG8_MMA(ai, bj, At, Bt) do { __builtin_amdgcn_s_setprio(1); _Pragma("unroll") for (int m = 0; m < 4; ++m) _Pragma("unroll") for (int n = 0; n < 2; ++n) _Pragma("unroll") for (int k = 0; k < 2; ++k) \
;         acc[ai][bj][m][n] = __builtin_amdgcn_mfma_f32_16x16x32_bf16(Bt[n][k], At[m][k], acc[ai][bj][m][n], 0, 0, 0); __builtin_amdgcn_s_setprio(0); } while (0)
; #define PG8_WAIT_V(n) asm volatile("s_waitcnt vmcnt(" #n ")" ::: "memory")
; #define PG8_WAIT_L(n) asm volatile("s_waitcnt lgkmcnt(" #n ")" ::: "memory")
; template <class Epi, class Sched, bool ALIGN_EPI = false, bool SP2 = false>
; __device__ __forceinline__ void gemm_phase(PG8_LAS unsigned char* lds, const Gemm g, const Sched& S, const Epi& E, int wave_in) {
;     ...
;             const bool last = (t == nt - 2);
;             const char* a1 = cA + (size_t)(t + 1) * kstep;
;             const char* a2 = last ? nA : cA + (size_t)(t + 2) * kstep; const char* b2 = last ? nB : cB + (size_t)(t + 2) * kstep;
;             const char* a3 = a2 + kstep; const char* b3 = b2 + kstep;
;             if (last && has_next) S.a_ready(nxt);
;             if constexpr (SP2) {
;             PG8_LDB(B0, 0, 0); PG8_LDB(B1, 0, 1); PG8_SCHED; PG8_LDA(At, 0, 0); PG8_STAGE(PG8_SA(1, 1), a1 + hstepA, voffA);
;             PG8_WAIT_V(8); PG8_WAIT_L(0); PG8_BAR; PG8_MMA(0, 0, At, B0); PG8_MMA(0, 1, At, B1); PG8_BAR; PG8_SCHED;
;             PG8_LDA(At, 0, 1); PG8_STAGE(PG8_SB(0, 0), b2, voffB); PG8_STAGE(PG8_SB(0, 1), b2 + hstep, voffB); PG8_STAGE(PG8_SA(0, 0), a2, voffA);
;             PG8_WAIT_V(8); PG8_WAIT_L(0); PG8_BAR; PG8_MMA(1, 0, At, B0); PG8_MMA(1, 1, At, B1); PG8_BAR; PG8_SCHED;
.LBB0_128:
	s_add_u32 s24, s22, 0xfffe0080
	s_addc_u32 s25, s23, -1
	s_add_i32 s47, 0, 0x10000
	s_cmp_eq_u32 s46, 4
	s_cselect_b32 s27, s17, s25
	s_cselect_b32 s26, s42, s24
	s_cselect_b32 s25, s11, s45
	s_cselect_b32 s24, s43, s44
	s_add_i32 s50, 0, 0x14000
	v_add_u32_e32 v70, s47, v171
	v_add_u32_e32 v156, s50, v171
	ds_read_b128 v[58:61], v70
	ds_read_b128 v[62:65], v70 offset:1024
	ds_read_b128 v[66:69], v70 offset:2048
	ds_read_b128 v[70:73], v70 offset:3072
	ds_read_b128 v[174:177], v156
	ds_read_b128 v[178:181], v156 offset:1024
	ds_read_b128 v[182:185], v156 offset:2048
	ds_read_b128 v[186:189], v156 offset:3072
	v_lshl_add_u64 v[156:157], s[22:23], 0, v[152:153]
	s_add_i32 m0, s31, 0xc000
	ds_read_b128 v[190:193], v173
	ds_read_b128 v[212:215], v173 offset:1024
	ds_read_b128 v[216:219], v173 offset:2048
	ds_read_b128 v[220:223], v173 offset:3072
	ds_read_b128 v[224:227], v173 offset:4096
	ds_read_b128 v[228:231], v173 offset:5120
	ds_read_b128 v[232:235], v173 offset:6144
	ds_read_b128 v[236:239], v173 offset:7168
	global_load_lds_dwordx4 v[156:157], off
	v_lshl_add_u64 v[156:157], s[22:23], 0, v[154:155]
	s_add_i32 m0, s31, 0xe000
	s_nop 0
	global_load_lds_dwordx4 v[156:157], off
	s_waitcnt vmcnt(8) lgkmcnt(0)
	s_barrier
	v_mfma_f32_16x16x32_bf16 v[142:145], v[58:61], v[190:193], v[142:145]
	v_mfma_f32_16x16x32_bf16 v[138:141], v[66:69], v[190:193], v[138:141]
	v_mfma_f32_16x16x32_bf16 v[126:129], v[58:61], v[216:219], v[126:129]
	v_mfma_f32_16x16x32_bf16 v[122:125], v[66:69], v[216:219], v[122:125]
	v_mfma_f32_16x16x32_bf16 v[110:113], v[58:61], v[224:227], v[110:113]
	v_mfma_f32_16x16x32_bf16 v[106:109], v[66:69], v[224:227], v[106:109]
	v_mfma_f32_16x16x32_bf16 v[94:97], v[58:61], v[232:235], v[94:97]
	v_mfma_f32_16x16x32_bf16 v[90:93], v[66:69], v[232:235], v[90:93]
	v_mfma_f32_16x16x32_bf16 v[142:145], v[62:65], v[212:215], v[142:145]
	v_mfma_f32_16x16x32_bf16 v[138:141], v[70:73], v[212:215], v[138:141]
	v_mfma_f32_16x16x32_bf16 v[126:129], v[62:65], v[220:223], v[126:129]
	v_mfma_f32_16x16x32_bf16 v[122:125], v[70:73], v[220:223], v[122:125]
	v_mfma_f32_16x16x32_bf16 v[110:113], v[62:65], v[228:231], v[110:113]
	v_mfma_f32_16x16x32_bf16 v[106:109], v[70:73], v[228:231], v[106:109]
	v_mfma_f32_16x16x32_bf16 v[94:97], v[62:65], v[236:239], v[94:97]
	v_mfma_f32_16x16x32_bf16 v[90:93], v[70:73], v[236:239], v[90:93]
	v_mfma_f32_16x16x32_bf16 v[134:137], v[174:177], v[190:193], v[134:137]
	v_mfma_f32_16x16x32_bf16 v[130:133], v[182:185], v[190:193], v[130:133]
	v_mfma_f32_16x16x32_bf16 v[118:121], v[174:177], v[216:219], v[118:121]
	v_mfma_f32_16x16x32_bf16 v[114:117], v[182:185], v[216:219], v[114:117]
	v_mfma_f32_16x16x32_bf16 v[102:105], v[174:177], v[224:227], v[102:105]
	v_mfma_f32_16x16x32_bf16 v[98:101], v[182:185], v[224:227], v[98:101]
	v_mfma_f32_16x16x32_bf16 v[86:89], v[174:177], v[232:235], v[86:89]
	v_mfma_f32_16x16x32_bf16 v[82:85], v[182:185], v[232:235], v[82:85]
	v_mfma_f32_16x16x32_bf16 v[134:137], v[178:181], v[212:215], v[134:137]
	v_mfma_f32_16x16x32_bf16 v[130:133], v[186:189], v[212:215], v[130:133]
	v_mfma_f32_16x16x32_bf16 v[118:121], v[178:181], v[220:223], v[118:121]
	v_mfma_f32_16x16x32_bf16 v[114:117], v[186:189], v[220:223], v[114:117]
	v_mfma_f32_16x16x32_bf16 v[102:105], v[178:181], v[228:231], v[102:105]
	v_mfma_f32_16x16x32_bf16 v[98:101], v[186:189], v[228:231], v[98:101]
	v_mfma_f32_16x16x32_bf16 v[86:89], v[178:181], v[236:239], v[86:89]
	v_mfma_f32_16x16x32_bf16 v[82:85], v[186:189], v[236:239], v[82:85]
	s_barrier
	s_add_i32 s47, s47, s30
	v_lshl_add_u64 v[156:157], s[24:25], 0, v[0:1]
	s_mov_b32 m0, s47
	ds_read_b128 v[190:193], v173 offset:16384
	ds_read_b128 v[212:215], v173 offset:17408
	ds_read_b128 v[216:219], v173 offset:18432
	ds_read_b128 v[220:223], v173 offset:19456
	ds_read_b128 v[224:227], v173 offset:20480
	ds_read_b128 v[228:231], v173 offset:21504
	ds_read_b128 v[232:235], v173 offset:22528
	ds_read_b128 v[236:239], v173 offset:23552
	global_load_lds_dwordx4 v[156:157], off
	s_add_i32 m0, s47, 0x2000
	s_add_u32 s48, s24, 0x20000
	v_lshl_add_u64 v[168:169], s[24:25], 0, v[146:147]
	s_addc_u32 s49, s25, 0
	s_add_i32 s47, s50, s30
	global_load_lds_dwordx4 v[168:169], off
	v_lshl_add_u64 v[240:241], s[48:49], 0, v[0:1]
	s_mov_b32 m0, s47
	v_lshl_add_u64 v[242:243], s[26:27], 0, v[148:149]
	global_load_lds_dwordx4 v[240:241], off
	v_lshl_add_u64 v[240:241], s[48:49], 0, v[146:147]
	s_add_i32 m0, s47, 0x2000
	s_nop 0
	global_load_lds_dwordx4 v[240:241], off
	v_lshl_add_u64 v[240:241], s[26:27], 0, v[150:151]
	s_mov_b32 m0, s31
	s_nop 0
	global_load_lds_dwordx4 v[240:241], off
	s_mov_b32 m0, s34
	s_nop 0
	global_load_lds_dwordx4 v[242:243], off
	s_waitcnt vmcnt(8) lgkmcnt(0)
	s_barrier
; #define PG8_STAGE(bufoff, gbase, voff) do { _Pragma("unroll") for (int _i = 0; _i < 2; ++_i) \
;         __builtin_amdgcn_global_load_lds((const unsigned*)((const char*)(gbase) + (voff)[_i]), (PG8_LAS unsigned*)(lds + (bufoff) + ldsw + _i * 8192), 16, 0, 0); } while (0)
; #define PG8_LDA(dst, b, h) do { _Pragma("unroll") for (int m = 0; m < 4; ++m) _Pragma("unroll") for (int k = 0; k < 2; ++k) dst[m][k] = *(const PG8_LAS bf16x8*)(lds + PG8_SA(b, h) + aoff + m * 2048 + k * 1024); } while (0)
; #define PG8_LDB(dst, b, h) do { _Pragma("unroll") for (int n = 0; n < 2; ++n) _Pragma("unroll") for (int k = 0; k < 2; ++k) dst[n][k] = *(const PG8_LAS bf16x8*)(lds + PG8_SB(b, h) + boff + n * 2048 + k * 1024); } while (0)
; #define PG8_MMA(ai, bj, At, Bt) do { __builtin_amdgcn_s_setprio(1); _Pragma("unroll") for (int m = 0; m < 4; ++m) _Pragma("unroll") for (int n = 0; n < 2; ++n) _Pragma("unroll") for (int k = 0; k < 2; ++k) \
;         acc[ai][bj][m][n] = __builtin_amdgcn_mfma_f32_16x16x32_bf16(Bt[n][k], At[m][k], acc[ai][bj][m][n], 0, 0, 0); __builtin_amdgcn_s_setprio(0); } while (0)
; #define PG8_WAIT_V(n) asm volatile("s_waitcnt vmcnt(" #n ")" ::: "memory")
; #define PG8_WAIT_L(n) asm volatile("s_waitcnt lgkmcnt(" #n ")" ::: "memory")
; #define PG8_BAR __builtin_amdgcn_s_barrier()
; #define PG8_SCHED __builtin_amdgcn_sched_barrier(0)
; template <class Epi, class Sched, bool ALIGN_EPI = false, bool SP2 = false>
; __device__ __forceinline__ void gemm_phase(PG8_LAS unsigned char* lds, const Gemm g, const Sched& S, const Epi& E, int wave_in) {
;     ...
;             PG8_WAIT_V(8); PG8_WAIT_L(0); PG8_BAR; PG8_MMA(1, 0, At, B0); PG8_MMA(1, 1, At, B1); PG8_BAR; PG8_SCHED;
;             PG8_LDB(B0, 1, 0); PG8_LDB(B1, 1, 1); PG8_SCHED; PG8_LDA(At, 1, 0); PG8_STAGE(PG8_SA(0, 1), a2 + hstepA, voffA);
;             PG8_WAIT_V(8); PG8_WAIT_L(0); PG8_BAR; PG8_MMA(0, 0, At, B0); PG8_MMA(0, 1, At, B1); PG8_BAR; PG8_SCHED;
	v_mfma_f32_16x16x32_bf16 v[78:81], v[58:61], v[190:193], v[78:81]
	v_mfma_f32_16x16x32_bf16 v[74:77], v[66:69], v[190:193], v[74:77]
	v_mfma_f32_16x16x32_bf16 v[46:49], v[58:61], v[216:219], v[46:49]
	v_mfma_f32_16x16x32_bf16 v[42:45], v[66:69], v[216:219], v[42:45]
	v_mfma_f32_16x16x32_bf16 v[30:33], v[58:61], v[224:227], v[30:33]
	v_mfma_f32_16x16x32_bf16 v[26:29], v[66:69], v[224:227], v[26:29]
	v_mfma_f32_16x16x32_bf16 v[14:17], v[58:61], v[232:235], v[14:17]
	v_mfma_f32_16x16x32_bf16 v[10:13], v[66:69], v[232:235], v[10:13]
	v_mfma_f32_16x16x32_bf16 v[78:81], v[62:65], v[212:215], v[78:81]
	v_mfma_f32_16x16x32_bf16 v[74:77], v[70:73], v[212:215], v[74:77]
	v_mfma_f32_16x16x32_bf16 v[46:49], v[62:65], v[220:223], v[46:49]
	v_mfma_f32_16x16x32_bf16 v[42:45], v[70:73], v[220:223], v[42:45]
	v_mfma_f32_16x16x32_bf16 v[30:33], v[62:65], v[228:231], v[30:33]
	v_mfma_f32_16x16x32_bf16 v[26:29], v[70:73], v[228:231], v[26:29]
	v_mfma_f32_16x16x32_bf16 v[14:17], v[62:65], v[236:239], v[14:17]
	v_mfma_f32_16x16x32_bf16 v[10:13], v[70:73], v[236:239], v[10:13]
	v_mfma_f32_16x16x32_bf16 v[54:57], v[174:177], v[190:193], v[54:57]
	v_mfma_f32_16x16x32_bf16 v[50:53], v[182:185], v[190:193], v[50:53]
	v_mfma_f32_16x16x32_bf16 v[38:41], v[174:177], v[216:219], v[38:41]
	v_mfma_f32_16x16x32_bf16 v[34:37], v[182:185], v[216:219], v[34:37]
	v_mfma_f32_16x16x32_bf16 v[22:25], v[174:177], v[224:227], v[22:25]
	v_mfma_f32_16x16x32_bf16 v[18:21], v[182:185], v[224:227], v[18:21]
	v_mfma_f32_16x16x32_bf16 v[6:9], v[174:177], v[232:235], v[6:9]
	v_mfma_f32_16x16x32_bf16 v[2:5], v[182:185], v[232:235], v[2:5]
	v_mfma_f32_16x16x32_bf16 v[54:57], v[178:181], v[212:215], v[54:57]
	v_mfma_f32_16x16x32_bf16 v[50:53], v[186:189], v[212:215], v[50:53]
	v_mfma_f32_16x16x32_bf16 v[38:41], v[178:181], v[220:223], v[38:41]
	v_mfma_f32_16x16x32_bf16 v[34:37], v[186:189], v[220:223], v[34:37]
	v_mfma_f32_16x16x32_bf16 v[22:25], v[178:181], v[228:231], v[22:25]
	v_mfma_f32_16x16x32_bf16 v[18:21], v[186:189], v[228:231], v[18:21]
	v_mfma_f32_16x16x32_bf16 v[6:9], v[178:181], v[236:239], v[6:9]
	v_mfma_f32_16x16x32_bf16 v[2:5], v[186:189], v[236:239], v[2:5]
	s_barrier
	s_add_i32 s47, 0, 0x18000
	s_add_i32 s48, 0, 0x1c000
	v_add_u32_e32 v70, s47, v171
	v_add_u32_e32 v186, s48, v171
	ds_read_b128 v[58:61], v70
	ds_read_b128 v[62:65], v70 offset:1024
	ds_read_b128 v[66:69], v70 offset:2048
	ds_read_b128 v[70:73], v70 offset:3072
	ds_read_b128 v[174:177], v186
	ds_read_b128 v[178:181], v186 offset:1024
	ds_read_b128 v[182:185], v186 offset:2048
	ds_read_b128 v[186:189], v186 offset:3072
	s_add_u32 s26, s26, 0x20000
	s_addc_u32 s27, s27, 0
	s_mov_b32 m0, s35
	v_lshl_add_u64 v[244:245], s[26:27], 0, v[150:151]
	ds_read_b128 v[190:193], v173 offset:32768
	ds_read_b128 v[212:215], v173 offset:33792
	ds_read_b128 v[216:219], v173 offset:34816
	ds_read_b128 v[220:223], v173 offset:35840
	ds_read_b128 v[224:227], v173 offset:36864
	ds_read_b128 v[228:231], v173 offset:37888
	ds_read_b128 v[232:235], v173 offset:38912
	ds_read_b128 v[236:239], v173 offset:39936
	global_load_lds_dwordx4 v[244:245], off
	v_lshl_add_u64 v[244:245], s[26:27], 0, v[148:149]
	s_mov_b32 m0, s36
	s_nop 0
	global_load_lds_dwordx4 v[244:245], off
	s_waitcnt vmcnt(8) lgkmcnt(0)
	s_barrier
	v_mfma_f32_16x16x32_bf16 v[142:145], v[58:61], v[190:193], v[142:145]
	v_mfma_f32_16x16x32_bf16 v[138:141], v[66:69], v[190:193], v[138:141]
	v_mfma_f32_16x16x32_bf16 v[126:129], v[58:61], v[216:219], v[126:129]
	v_mfma_f32_16x16x32_bf16 v[122:125], v[66:69], v[216:219], v[122:125]
	v_mfma_f32_16x16x32_bf16 v[110:113], v[58:61], v[224:227], v[110:113]
	v_mfma_f32_16x16x32_bf16 v[106:109], v[66:69], v[224:227], v[106:109]
	v_mfma_f32_16x16x32_bf16 v[94:97], v[58:61], v[232:235], v[94:97]
	v_mfma_f32_16x16x32_bf16 v[90:93], v[66:69], v[232:235], v[90:93]
	v_mfma_f32_16x16x32_bf16 v[142:145], v[62:65], v[212:215], v[142:145]
	v_mfma_f32_16x16x32_bf16 v[138:141], v[70:73], v[212:215], v[138:141]
	v_mfma_f32_16x16x32_bf16 v[126:129], v[62:65], v[220:223], v[126:129]
	v_mfma_f32_16x16x32_bf16 v[122:125], v[70:73], v[220:223], v[122:125]
	v_mfma_f32_16x16x32_bf16 v[110:113], v[62:65], v[228:231], v[110:113]
	v_mfma_f32_16x16x32_bf16 v[106:109], v[70:73], v[228:231], v[106:109]
	v_mfma_f32_16x16x32_bf16 v[94:97], v[62:65], v[236:239], v[94:97]
	v_mfma_f32_16x16x32_bf16 v[90:93], v[70:73], v[236:239], v[90:93]
	v_mfma_f32_16x16x32_bf16 v[134:137], v[174:177], v[190:193], v[134:137]
	v_mfma_f32_16x16x32_bf16 v[130:133], v[182:185], v[190:193], v[130:133]
	v_mfma_f32_16x16x32_bf16 v[118:121], v[174:177], v[216:219], v[118:121]
	v_mfma_f32_16x16x32_bf16 v[114:117], v[182:185], v[216:219], v[114:117]
	v_mfma_f32_16x16x32_bf16 v[102:105], v[174:177], v[224:227], v[102:105]
	v_mfma_f32_16x16x32_bf16 v[98:101], v[182:185], v[224:227], v[98:101]
	v_mfma_f32_16x16x32_bf16 v[86:89], v[174:177], v[232:235], v[86:89]
	v_mfma_f32_16x16x32_bf16 v[82:85], v[182:185], v[232:235], v[82:85]
	v_mfma_f32_16x16x32_bf16 v[134:137], v[178:181], v[212:215], v[134:137]
	v_mfma_f32_16x16x32_bf16 v[130:133], v[186:189], v[212:215], v[130:133]
	v_mfma_f32_16x16x32_bf16 v[118:121], v[178:181], v[220:223], v[118:121]
	v_mfma_f32_16x16x32_bf16 v[114:117], v[186:189], v[220:223], v[114:117]
	v_mfma_f32_16x16x32_bf16 v[102:105], v[178:181], v[228:231], v[102:105]
	v_mfma_f32_16x16x32_bf16 v[98:101], v[186:189], v[228:231], v[98:101]
	v_mfma_f32_16x16x32_bf16 v[86:89], v[178:181], v[236:239], v[86:89]
	v_mfma_f32_16x16x32_bf16 v[82:85], v[186:189], v[236:239], v[82:85]
	s_barrier
; #define PG8_STAGE(bufoff, gbase, voff) do { _Pragma("unroll") for (int _i = 0; _i < 2; ++_i) \
;         __builtin_amdgcn_global_load_lds((const unsigned*)((const char*)(gbase) + (voff)[_i]), (PG8_LAS unsigned*)(lds + (bufoff) + ldsw + _i * 8192), 16, 0, 0); } while (0)
; #define PG8_LDA(dst, b, h) do { _Pragma("unroll") for (int m = 0; m < 4; ++m) _Pragma("unroll") for (int k = 0; k < 2; ++k) dst[m][k] = *(const PG8_LAS bf16x8*)(lds + PG8_SA(b, h) + aoff + m * 2048 + k * 1024); } while (0)
; #define PG8_MMA(ai, bj, At, Bt) do { __builtin_amdgcn_s_setprio(1); _Pragma("unroll") for (int m = 0; m < 4; ++m) _Pragma("unroll") for (int n = 0; n < 2; ++n) _Pragma("unroll") for (int k = 0; k < 2; ++k) \
;         acc[ai][bj][m][n] = __builtin_amdgcn_mfma_f32_16x16x32_bf16(Bt[n][k], At[m][k], acc[ai][bj][m][n], 0, 0, 0); __builtin_amdgcn_s_setprio(0); } while (0)
; #define PG8_WAIT_V(n) asm volatile("s_waitcnt vmcnt(" #n ")" ::: "memory")
; #define PG8_WAIT_L(n) asm volatile("s_waitcnt lgkmcnt(" #n ")" ::: "memory")
; #define PG8_BAR __builtin_amdgcn_s_barrier()
; #define PG8_SCHED __builtin_amdgcn_sched_barrier(0)
; template <class Epi, class Sched, bool ALIGN_EPI = false, bool SP2 = false>
; __device__ __forceinline__ void gemm_phase(PG8_LAS unsigned char* lds, const Gemm g, const Sched& S, const Epi& E, int wave_in) {
;     ...
;             PG8_LDA(At, 1, 1); PG8_STAGE(PG8_SB(1, 0), b3, voffB); PG8_STAGE(PG8_SB(1, 1), b3 + hstep, voffB); PG8_STAGE(PG8_SA(1, 0), a3, voffA);
;             PG8_WAIT_V(8); PG8_WAIT_L(0); PG8_BAR; PG8_MMA(1, 0, At, B0); PG8_MMA(1, 1, At, B1); PG8_BAR; PG8_SCHED;
;     ...
;         if constexpr (ALIGN_EPI) { if (wr == 0) PG8_BAR; }
;         if constexpr (!Epi::AFTER_DRAIN) { E(acc, cur, wr, wc, fr, fq); S.done(cur); }
;         if (!has_next) break;
	s_add_i32 s26, s47, s30
	v_lshl_add_u64 v[156:157], v[156:157], 0, s[84:85]
	s_mov_b32 m0, s26
	ds_read_b128 v[190:193], v173 offset:49152
	ds_read_b128 v[212:215], v173 offset:50176
	ds_read_b128 v[216:219], v173 offset:51200
	ds_read_b128 v[220:223], v173 offset:52224
	ds_read_b128 v[224:227], v173 offset:53248
	ds_read_b128 v[228:231], v173 offset:54272
	ds_read_b128 v[232:235], v173 offset:55296
	ds_read_b128 v[236:239], v173 offset:56320
	global_load_lds_dwordx4 v[156:157], off
	s_add_i32 m0, s26, 0x2000
	s_add_u32 s24, s24, 0x20080
	v_lshl_add_u64 v[156:157], v[168:169], 0, s[84:85]
	s_addc_u32 s25, s25, 0
	s_add_i32 s26, s48, s30
	global_load_lds_dwordx4 v[156:157], off
	v_lshl_add_u64 v[156:157], s[24:25], 0, v[0:1]
	s_mov_b32 m0, s26
	s_nop 0
	global_load_lds_dwordx4 v[156:157], off
	v_lshl_add_u64 v[156:157], s[24:25], 0, v[146:147]
	s_add_i32 m0, s26, 0x2000
	s_nop 0
	global_load_lds_dwordx4 v[156:157], off
	v_lshl_add_u64 v[156:157], v[240:241], 0, s[84:85]
	s_mov_b32 m0, s37
	s_nop 0
	global_load_lds_dwordx4 v[156:157], off
	v_lshl_add_u64 v[156:157], v[242:243], 0, s[84:85]
	s_mov_b32 m0, s38
	s_nop 0
	global_load_lds_dwordx4 v[156:157], off
	s_waitcnt vmcnt(8) lgkmcnt(0)
	s_barrier
	v_mfma_f32_16x16x32_bf16 v[78:81], v[58:61], v[190:193], v[78:81]
	v_mfma_f32_16x16x32_bf16 v[74:77], v[66:69], v[190:193], v[74:77]
	v_mfma_f32_16x16x32_bf16 v[46:49], v[58:61], v[216:219], v[46:49]
	v_mfma_f32_16x16x32_bf16 v[42:45], v[66:69], v[216:219], v[42:45]
	v_mfma_f32_16x16x32_bf16 v[30:33], v[58:61], v[224:227], v[30:33]
	v_mfma_f32_16x16x32_bf16 v[26:29], v[66:69], v[224:227], v[26:29]
	v_mfma_f32_16x16x32_bf16 v[14:17], v[58:61], v[232:235], v[14:17]
	v_mfma_f32_16x16x32_bf16 v[10:13], v[66:69], v[232:235], v[10:13]
	v_mfma_f32_16x16x32_bf16 v[78:81], v[62:65], v[212:215], v[78:81]
	v_mfma_f32_16x16x32_bf16 v[74:77], v[70:73], v[212:215], v[74:77]
	v_mfma_f32_16x16x32_bf16 v[46:49], v[62:65], v[220:223], v[46:49]
	v_mfma_f32_16x16x32_bf16 v[42:45], v[70:73], v[220:223], v[42:45]
	v_mfma_f32_16x16x32_bf16 v[30:33], v[62:65], v[228:231], v[30:33]
	v_mfma_f32_16x16x32_bf16 v[26:29], v[70:73], v[228:231], v[26:29]
	v_mfma_f32_16x16x32_bf16 v[14:17], v[62:65], v[236:239], v[14:17]
	v_mfma_f32_16x16x32_bf16 v[10:13], v[70:73], v[236:239], v[10:13]
	v_mfma_f32_16x16x32_bf16 v[54:57], v[174:177], v[190:193], v[54:57]
	v_mfma_f32_16x16x32_bf16 v[50:53], v[182:185], v[190:193], v[50:53]
	v_mfma_f32_16x16x32_bf16 v[38:41], v[174:177], v[216:219], v[38:41]
	v_mfma_f32_16x16x32_bf16 v[34:37], v[182:185], v[216:219], v[34:37]
	v_mfma_f32_16x16x32_bf16 v[22:25], v[174:177], v[224:227], v[22:25]
	v_mfma_f32_16x16x32_bf16 v[18:21], v[182:185], v[224:227], v[18:21]
	v_mfma_f32_16x16x32_bf16 v[6:9], v[174:177], v[232:235], v[6:9]
	v_mfma_f32_16x16x32_bf16 v[2:5], v[182:185], v[232:235], v[2:5]
	v_mfma_f32_16x16x32_bf16 v[54:57], v[178:181], v[212:215], v[54:57]
	v_mfma_f32_16x16x32_bf16 v[50:53], v[186:189], v[212:215], v[50:53]
	v_mfma_f32_16x16x32_bf16 v[38:41], v[178:181], v[220:223], v[38:41]
	v_mfma_f32_16x16x32_bf16 v[34:37], v[186:189], v[220:223], v[34:37]
	v_mfma_f32_16x16x32_bf16 v[22:25], v[178:181], v[228:231], v[22:25]
	v_mfma_f32_16x16x32_bf16 v[18:21], v[186:189], v[228:231], v[18:21]
	v_mfma_f32_16x16x32_bf16 v[6:9], v[178:181], v[236:239], v[6:9]
	v_mfma_f32_16x16x32_bf16 v[2:5], v[186:189], v[236:239], v[2:5]
	s_barrier
	s_add_i32 s46, s46, 2
	s_add_u32 s22, s22, 0x100
	s_addc_u32 s23, s23, 0
	s_add_u32 s44, s44, 0x100
	s_addc_u32 s45, s45, 0
	s_cmp_gt_u32 s46, 5
	s_cbranch_scc0 .LBB0_128
	s_and_b64 vcc, exec, s[8:9]
	v_readlane_b32 s26, v254, 6
	v_readlane_b32 s27, v254, 7
	s_cbranch_vccz .LBB0_131
	s_barrier

; #define PG8_STAGE(bufoff, gbase, voff) do { _Pragma("unroll") for (int _i = 0; _i < 2; ++_i) \
;         __builtin_amdgcn_global_load_lds((const unsigned*)((const char*)(gbase) + (voff)[_i]), (PG8_LAS unsigned*)(lds + (bufoff) + ldsw + _i * 8192), 16, 0, 0); } while (0)
; #define PG8_LDA(dst, b, h) do { _Pragma("unroll") for (int m = 0; m < 4; ++m) _Pragma("unroll") for (int k = 0; k < 2; ++k) dst[m][k] = *(const PG8_LAS bf16x8*)(lds + PG8_SA(b, h) + aoff + m * 2048 + k * 1024); } while (0)
; #define PG8_LDB(dst, b, h) do { _Pragma("unroll") for (int n = 0; n < 2; ++n) _Pragma("unroll") for (int k = 0; k < 2; ++k) dst[n][k] = *(const PG8_LAS bf16x8*)(lds + PG8_SB(b, h) + boff + n * 2048 + k * 1024); } while (0)
; #define PG8_MMA(ai, bj, At, Bt) do { __builtin_amdgcn_s_setprio(1); _Pragma("unroll") for (int m = 0; m < 4; ++m) _Pragma("unroll") for (int n = 0; n < 2; ++n) _Pragma("unroll") for (int k = 0; k < 2; ++k) \
;         acc[ai][bj][m][n] = __builtin_amdgcn_mfma_f32_16x16x32_bf16(Bt[n][k], At[m][k], acc[ai][bj][m][n], 0, 0, 0); __builtin_amdgcn_s_setprio(0); } while (0)
; #define PG8_WAIT_V(n) asm volatile("s_waitcnt vmcnt(" #n ")" ::: "memory")
; #define PG8_WAIT_L(n) asm volatile("s_waitcnt lgkmcnt(" #n ")" ::: "memory")
; template <class Epi, class Sched, bool ALIGN_EPI = false, bool SP2 = false>
; __device__ __forceinline__ void gemm_phase(PG8_LAS unsigned char* lds, const Gemm g, const Sched& S, const Epi& E, int wave_in) {
;     ...
;             const bool last = (t == nt - 2);
;             const char* a1 = cA + (size_t)(t + 1) * kstep;
;             const char* a2 = last ? nA : cA + (size_t)(t + 2) * kstep; const char* b2 = last ? nB : cB + (size_t)(t + 2) * kstep;
;             const char* a3 = a2 + kstep; const char* b3 = b2 + kstep;
;             if (last && has_next) S.a_ready(nxt);
;             if constexpr (SP2) {
;             PG8_LDB(B0, 0, 0); PG8_LDB(B1, 0, 1); PG8_SCHED; PG8_LDA(At, 0, 0); PG8_STAGE(PG8_SA(1, 1), a1 + hstepA, voffA);
;             PG8_WAIT_V(8); PG8_WAIT_L(0); PG8_BAR; PG8_MMA(0, 0, At, B0); PG8_MMA(0, 1, At, B1); PG8_BAR; PG8_SCHED;
;             PG8_LDA(At, 0, 1); PG8_STAGE(PG8_SB(0, 0), b2, voffB); PG8_STAGE(PG8_SB(0, 1), b2 + hstep, voffB); PG8_STAGE(PG8_SA(0, 0), a2, voffA);
;             PG8_WAIT_V(8); PG8_WAIT_L(0); PG8_BAR; PG8_MMA(1, 0, At, B0); PG8_MMA(1, 1, At, B1); PG8_BAR; PG8_SCHED;
.LBB0_277:
	s_add_u32 s2, s0, 0xfff80080
	s_addc_u32 s3, s1, -1
	s_add_i32 s41, 0, 0x10000
	s_cmp_eq_u32 s40, 28
	s_cselect_b32 s5, s19, s3
	s_cselect_b32 s4, s36, s2
	s_cselect_b32 s3, s17, s39
	s_cselect_b32 s2, s37, s38
	s_add_i32 s44, 0, 0x14000
	v_add_u32_e32 v46, s41, v181
	v_add_u32_e32 v156, s44, v181
	ds_read_b128 v[26:29], v46
	ds_read_b128 v[30:33], v46 offset:1024
	ds_read_b128 v[42:45], v46 offset:2048
	ds_read_b128 v[46:49], v46 offset:3072
	ds_read_b128 v[168:171], v156
	ds_read_b128 v[172:175], v156 offset:1024
	ds_read_b128 v[176:179], v156 offset:2048
	ds_read_b128 v[184:187], v156 offset:3072
	v_lshl_add_u64 v[156:157], s[0:1], 0, v[152:153]
	s_add_i32 m0, s25, 0xc000
	ds_read_b128 v[188:191], v183
	ds_read_b128 v[212:215], v183 offset:1024
	ds_read_b128 v[216:219], v183 offset:2048
	ds_read_b128 v[220:223], v183 offset:3072
	ds_read_b128 v[224:227], v183 offset:4096
	ds_read_b128 v[228:231], v183 offset:5120
	ds_read_b128 v[232:235], v183 offset:6144
	ds_read_b128 v[236:239], v183 offset:7168
	global_load_lds_dwordx4 v[156:157], off
	v_lshl_add_u64 v[156:157], s[0:1], 0, v[154:155]
	s_add_i32 m0, s25, 0xe000
	s_nop 0
	global_load_lds_dwordx4 v[156:157], off
	s_waitcnt vmcnt(8) lgkmcnt(0)
	s_barrier
	v_mfma_f32_16x16x32_bf16 v[142:145], v[26:29], v[188:191], v[142:145]
	v_mfma_f32_16x16x32_bf16 v[138:141], v[42:45], v[188:191], v[138:141]
	v_mfma_f32_16x16x32_bf16 v[126:129], v[26:29], v[216:219], v[126:129]
	v_mfma_f32_16x16x32_bf16 v[122:125], v[42:45], v[216:219], v[122:125]
	v_mfma_f32_16x16x32_bf16 v[110:113], v[26:29], v[224:227], v[110:113]
	v_mfma_f32_16x16x32_bf16 v[106:109], v[42:45], v[224:227], v[106:109]
	v_mfma_f32_16x16x32_bf16 v[94:97], v[26:29], v[232:235], v[94:97]
	v_mfma_f32_16x16x32_bf16 v[90:93], v[42:45], v[232:235], v[90:93]
	v_mfma_f32_16x16x32_bf16 v[142:145], v[30:33], v[212:215], v[142:145]
	v_mfma_f32_16x16x32_bf16 v[138:141], v[46:49], v[212:215], v[138:141]
	v_mfma_f32_16x16x32_bf16 v[126:129], v[30:33], v[220:223], v[126:129]
	v_mfma_f32_16x16x32_bf16 v[122:125], v[46:49], v[220:223], v[122:125]
	v_mfma_f32_16x16x32_bf16 v[110:113], v[30:33], v[228:231], v[110:113]
	v_mfma_f32_16x16x32_bf16 v[106:109], v[46:49], v[228:231], v[106:109]
	v_mfma_f32_16x16x32_bf16 v[94:97], v[30:33], v[236:239], v[94:97]
	v_mfma_f32_16x16x32_bf16 v[90:93], v[46:49], v[236:239], v[90:93]
	v_mfma_f32_16x16x32_bf16 v[134:137], v[168:171], v[188:191], v[134:137]
	v_mfma_f32_16x16x32_bf16 v[130:133], v[176:179], v[188:191], v[130:133]
	v_mfma_f32_16x16x32_bf16 v[118:121], v[168:171], v[216:219], v[118:121]
	v_mfma_f32_16x16x32_bf16 v[114:117], v[176:179], v[216:219], v[114:117]
	v_mfma_f32_16x16x32_bf16 v[102:105], v[168:171], v[224:227], v[102:105]
	v_mfma_f32_16x16x32_bf16 v[98:101], v[176:179], v[224:227], v[98:101]
	v_mfma_f32_16x16x32_bf16 v[86:89], v[168:171], v[232:235], v[86:89]
	v_mfma_f32_16x16x32_bf16 v[82:85], v[176:179], v[232:235], v[82:85]
	v_mfma_f32_16x16x32_bf16 v[134:137], v[172:175], v[212:215], v[134:137]
	v_mfma_f32_16x16x32_bf16 v[130:133], v[184:187], v[212:215], v[130:133]
	v_mfma_f32_16x16x32_bf16 v[118:121], v[172:175], v[220:223], v[118:121]
	v_mfma_f32_16x16x32_bf16 v[114:117], v[184:187], v[220:223], v[114:117]
	v_mfma_f32_16x16x32_bf16 v[102:105], v[172:175], v[228:231], v[102:105]
	v_mfma_f32_16x16x32_bf16 v[98:101], v[184:187], v[228:231], v[98:101]
	v_mfma_f32_16x16x32_bf16 v[86:89], v[172:175], v[236:239], v[86:89]
	v_mfma_f32_16x16x32_bf16 v[82:85], v[184:187], v[236:239], v[82:85]
	s_barrier
	s_add_i32 s41, s41, s24
	v_lshl_add_u64 v[156:157], s[2:3], 0, v[0:1]
	s_mov_b32 m0, s41
	ds_read_b128 v[188:191], v183 offset:16384
	ds_read_b128 v[212:215], v183 offset:17408
	ds_read_b128 v[216:219], v183 offset:18432
	ds_read_b128 v[220:223], v183 offset:19456
	ds_read_b128 v[224:227], v183 offset:20480
	ds_read_b128 v[228:231], v183 offset:21504
	ds_read_b128 v[232:235], v183 offset:22528
	ds_read_b128 v[236:239], v183 offset:23552
	global_load_lds_dwordx4 v[156:157], off
	s_add_i32 m0, s41, 0x2000
	s_add_u32 s42, s2, 0x80000
	v_lshl_add_u64 v[192:193], s[2:3], 0, v[146:147]
	s_addc_u32 s43, s3, 0
	s_add_i32 s41, s44, s24
	global_load_lds_dwordx4 v[192:193], off
	v_lshl_add_u64 v[240:241], s[42:43], 0, v[0:1]
	s_mov_b32 m0, s41
	v_lshl_add_u64 v[242:243], s[4:5], 0, v[148:149]
	global_load_lds_dwordx4 v[240:241], off
	v_lshl_add_u64 v[240:241], s[42:43], 0, v[146:147]
	s_add_i32 m0, s41, 0x2000
	s_nop 0
	global_load_lds_dwordx4 v[240:241], off
	v_lshl_add_u64 v[240:241], s[4:5], 0, v[150:151]
	s_mov_b32 m0, s25
	s_nop 0
	global_load_lds_dwordx4 v[240:241], off
	s_mov_b32 m0, s26
	s_nop 0
	global_load_lds_dwordx4 v[242:243], off
	s_waitcnt vmcnt(8) lgkmcnt(0)
	s_barrier
; #define PG8_STAGE(bufoff, gbase, voff) do { _Pragma("unroll") for (int _i = 0; _i < 2; ++_i) \
;         __builtin_amdgcn_global_load_lds((const unsigned*)((const char*)(gbase) + (voff)[_i]), (PG8_LAS unsigned*)(lds + (bufoff) + ldsw + _i * 8192), 16, 0, 0); } while (0)
; #define PG8_LDA(dst, b, h) do { _Pragma("unroll") for (int m = 0; m < 4; ++m) _Pragma("unroll") for (int k = 0; k < 2; ++k) dst[m][k] = *(const PG8_LAS bf16x8*)(lds + PG8_SA(b, h) + aoff + m * 2048 + k * 1024); } while (0)
; #define PG8_LDB(dst, b, h) do { _Pragma("unroll") for (int n = 0; n < 2; ++n) _Pragma("unroll") for (int k = 0; k < 2; ++k) dst[n][k] = *(const PG8_LAS bf16x8*)(lds + PG8_SB(b, h) + boff + n * 2048 + k * 1024); } while (0)
; #define PG8_MMA(ai, bj, At, Bt) do { __builtin_amdgcn_s_setprio(1); _Pragma("unroll") for (int m = 0; m < 4; ++m) _Pragma("unroll") for (int n = 0; n < 2; ++n) _Pragma("unroll") for (int k = 0; k < 2; ++k) \
;         acc[ai][bj][m][n] = __builtin_amdgcn_mfma_f32_16x16x32_bf16(Bt[n][k], At[m][k], acc[ai][bj][m][n], 0, 0, 0); __builtin_amdgcn_s_setprio(0); } while (0)
; #define PG8_WAIT_V(n) asm volatile("s_waitcnt vmcnt(" #n ")" ::: "memory")
; #define PG8_WAIT_L(n) asm volatile("s_waitcnt lgkmcnt(" #n ")" ::: "memory")
; #define PG8_BAR __builtin_amdgcn_s_barrier()
; #define PG8_SCHED __builtin_amdgcn_sched_barrier(0)
; template <class Epi, class Sched, bool ALIGN_EPI = false, bool SP2 = false>
; __device__ __forceinline__ void gemm_phase(PG8_LAS unsigned char* lds, const Gemm g, const Sched& S, const Epi& E, int wave_in) {
;     ...
;             PG8_WAIT_V(8); PG8_WAIT_L(0); PG8_BAR; PG8_MMA(1, 0, At, B0); PG8_MMA(1, 1, At, B1); PG8_BAR; PG8_SCHED;
;             PG8_LDB(B0, 1, 0); PG8_LDB(B1, 1, 1); PG8_SCHED; PG8_LDA(At, 1, 0); PG8_STAGE(PG8_SA(0, 1), a2 + hstepA, voffA);
;             PG8_WAIT_V(8); PG8_WAIT_L(0); PG8_BAR; PG8_MMA(0, 0, At, B0); PG8_MMA(0, 1, At, B1); PG8_BAR; PG8_SCHED;
	v_mfma_f32_16x16x32_bf16 v[78:81], v[26:29], v[188:191], v[78:81]
	v_mfma_f32_16x16x32_bf16 v[74:77], v[42:45], v[188:191], v[74:77]
	v_mfma_f32_16x16x32_bf16 v[62:65], v[26:29], v[216:219], v[62:65]
	v_mfma_f32_16x16x32_bf16 v[58:61], v[42:45], v[216:219], v[58:61]
	v_mfma_f32_16x16x32_bf16 v[38:41], v[26:29], v[224:227], v[38:41]
	v_mfma_f32_16x16x32_bf16 v[34:37], v[42:45], v[224:227], v[34:37]
	v_mfma_f32_16x16x32_bf16 v[14:17], v[26:29], v[232:235], v[14:17]
	v_mfma_f32_16x16x32_bf16 v[10:13], v[42:45], v[232:235], v[10:13]
	v_mfma_f32_16x16x32_bf16 v[78:81], v[30:33], v[212:215], v[78:81]
	v_mfma_f32_16x16x32_bf16 v[74:77], v[46:49], v[212:215], v[74:77]
	v_mfma_f32_16x16x32_bf16 v[62:65], v[30:33], v[220:223], v[62:65]
	v_mfma_f32_16x16x32_bf16 v[58:61], v[46:49], v[220:223], v[58:61]
	v_mfma_f32_16x16x32_bf16 v[38:41], v[30:33], v[228:231], v[38:41]
	v_mfma_f32_16x16x32_bf16 v[34:37], v[46:49], v[228:231], v[34:37]
	v_mfma_f32_16x16x32_bf16 v[14:17], v[30:33], v[236:239], v[14:17]
	v_mfma_f32_16x16x32_bf16 v[10:13], v[46:49], v[236:239], v[10:13]
	v_mfma_f32_16x16x32_bf16 v[22:25], v[168:171], v[224:227], v[22:25]
	v_mfma_f32_16x16x32_bf16 v[18:21], v[176:179], v[224:227], v[18:21]
	v_mfma_f32_16x16x32_bf16 v[6:9], v[168:171], v[232:235], v[6:9]
	v_mfma_f32_16x16x32_bf16 v[2:5], v[176:179], v[232:235], v[2:5]
	v_mfma_f32_16x16x32_bf16 v[26:29], v[168:171], v[188:191], v[70:73]
	v_mfma_f32_16x16x32_bf16 v[30:33], v[176:179], v[188:191], v[66:69]
	v_mfma_f32_16x16x32_bf16 v[42:45], v[168:171], v[216:219], v[54:57]
	v_mfma_f32_16x16x32_bf16 v[46:49], v[176:179], v[216:219], v[50:53]
	v_mfma_f32_16x16x32_bf16 v[22:25], v[172:175], v[228:231], v[22:25]
	v_mfma_f32_16x16x32_bf16 v[18:21], v[184:187], v[228:231], v[18:21]
	v_mfma_f32_16x16x32_bf16 v[6:9], v[172:175], v[236:239], v[6:9]
	v_mfma_f32_16x16x32_bf16 v[2:5], v[184:187], v[236:239], v[2:5]
	v_mfma_f32_16x16x32_bf16 v[26:29], v[172:175], v[212:215], v[26:29]
	v_mfma_f32_16x16x32_bf16 v[30:33], v[184:187], v[212:215], v[30:33]
	v_mfma_f32_16x16x32_bf16 v[42:45], v[172:175], v[220:223], v[42:45]
	v_mfma_f32_16x16x32_bf16 v[46:49], v[184:187], v[220:223], v[46:49]
	s_barrier
	s_add_i32 s41, 0, 0x18000
	s_add_i32 s42, 0, 0x1c000
	v_add_u32_e32 v70, s41, v181
	v_add_u32_e32 v184, s42, v181
	ds_read_b128 v[50:53], v70
	ds_read_b128 v[54:57], v70 offset:1024
	ds_read_b128 v[66:69], v70 offset:2048
	ds_read_b128 v[70:73], v70 offset:3072
	ds_read_b128 v[168:171], v184
	ds_read_b128 v[172:175], v184 offset:1024
	ds_read_b128 v[176:179], v184 offset:2048
	ds_read_b128 v[184:187], v184 offset:3072
	s_add_u32 s4, s4, 0x80000
	s_addc_u32 s5, s5, 0
	s_mov_b32 m0, s27
	v_lshl_add_u64 v[244:245], s[4:5], 0, v[150:151]
	ds_read_b128 v[188:191], v183 offset:32768
	ds_read_b128 v[212:215], v183 offset:33792
	ds_read_b128 v[216:219], v183 offset:34816
	ds_read_b128 v[220:223], v183 offset:35840
	ds_read_b128 v[224:227], v183 offset:36864
	ds_read_b128 v[228:231], v183 offset:37888
	ds_read_b128 v[232:235], v183 offset:38912
	ds_read_b128 v[236:239], v183 offset:39936
	global_load_lds_dwordx4 v[244:245], off
	v_lshl_add_u64 v[244:245], s[4:5], 0, v[148:149]
	s_mov_b32 m0, s28
	s_nop 0
	global_load_lds_dwordx4 v[244:245], off
	s_waitcnt vmcnt(8) lgkmcnt(0)
	s_barrier
	v_mfma_f32_16x16x32_bf16 v[142:145], v[50:53], v[188:191], v[142:145]
	v_mfma_f32_16x16x32_bf16 v[138:141], v[66:69], v[188:191], v[138:141]
	v_mfma_f32_16x16x32_bf16 v[126:129], v[50:53], v[216:219], v[126:129]
	v_mfma_f32_16x16x32_bf16 v[122:125], v[66:69], v[216:219], v[122:125]
	v_mfma_f32_16x16x32_bf16 v[110:113], v[50:53], v[224:227], v[110:113]
	v_mfma_f32_16x16x32_bf16 v[106:109], v[66:69], v[224:227], v[106:109]
	v_mfma_f32_16x16x32_bf16 v[94:97], v[50:53], v[232:235], v[94:97]
	v_mfma_f32_16x16x32_bf16 v[90:93], v[66:69], v[232:235], v[90:93]
	v_mfma_f32_16x16x32_bf16 v[142:145], v[54:57], v[212:215], v[142:145]
	v_mfma_f32_16x16x32_bf16 v[138:141], v[70:73], v[212:215], v[138:141]
	v_mfma_f32_16x16x32_bf16 v[126:129], v[54:57], v[220:223], v[126:129]
	v_mfma_f32_16x16x32_bf16 v[122:125], v[70:73], v[220:223], v[122:125]
	v_mfma_f32_16x16x32_bf16 v[110:113], v[54:57], v[228:231], v[110:113]
	v_mfma_f32_16x16x32_bf16 v[106:109], v[70:73], v[228:231], v[106:109]
	v_mfma_f32_16x16x32_bf16 v[94:97], v[54:57], v[236:239], v[94:97]
	v_mfma_f32_16x16x32_bf16 v[90:93], v[70:73], v[236:239], v[90:93]
	v_mfma_f32_16x16x32_bf16 v[134:137], v[168:171], v[188:191], v[134:137]
	v_mfma_f32_16x16x32_bf16 v[130:133], v[176:179], v[188:191], v[130:133]
	v_mfma_f32_16x16x32_bf16 v[118:121], v[168:171], v[216:219], v[118:121]
	v_mfma_f32_16x16x32_bf16 v[114:117], v[176:179], v[216:219], v[114:117]
	v_mfma_f32_16x16x32_bf16 v[102:105], v[168:171], v[224:227], v[102:105]
	v_mfma_f32_16x16x32_bf16 v[98:101], v[176:179], v[224:227], v[98:101]
	v_mfma_f32_16x16x32_bf16 v[86:89], v[168:171], v[232:235], v[86:89]
	v_mfma_f32_16x16x32_bf16 v[82:85], v[176:179], v[232:235], v[82:85]
	v_mfma_f32_16x16x32_bf16 v[134:137], v[172:175], v[212:215], v[134:137]
	v_mfma_f32_16x16x32_bf16 v[130:133], v[184:187], v[212:215], v[130:133]
	v_mfma_f32_16x16x32_bf16 v[118:121], v[172:175], v[220:223], v[118:121]
	v_mfma_f32_16x16x32_bf16 v[114:117], v[184:187], v[220:223], v[114:117]
	v_mfma_f32_16x16x32_bf16 v[102:105], v[172:175], v[228:231], v[102:105]
	v_mfma_f32_16x16x32_bf16 v[98:101], v[184:187], v[228:231], v[98:101]
	v_mfma_f32_16x16x32_bf16 v[86:89], v[172:175], v[236:239], v[86:89]
	v_mfma_f32_16x16x32_bf16 v[82:85], v[184:187], v[236:239], v[82:85]
	s_barrier
; #define PG8_STAGE(bufoff, gbase, voff) do { _Pragma("unroll") for (int _i = 0; _i < 2; ++_i) \
;         __builtin_amdgcn_global_load_lds((const unsigned*)((const char*)(gbase) + (voff)[_i]), (PG8_LAS unsigned*)(lds + (bufoff) + ldsw + _i * 8192), 16, 0, 0); } while (0)
; #define PG8_LDA(dst, b, h) do { _Pragma("unroll") for (int m = 0; m < 4; ++m) _Pragma("unroll") for (int k = 0; k < 2; ++k) dst[m][k] = *(const PG8_LAS bf16x8*)(lds + PG8_SA(b, h) + aoff + m * 2048 + k * 1024); } while (0)
; #define PG8_MMA(ai, bj, At, Bt) do { __builtin_amdgcn_s_setprio(1); _Pragma("unroll") for (int m = 0; m < 4; ++m) _Pragma("unroll") for (int n = 0; n < 2; ++n) _Pragma("unroll") for (int k = 0; k < 2; ++k) \
;         acc[ai][bj][m][n] = __builtin_amdgcn_mfma_f32_16x16x32_bf16(Bt[n][k], At[m][k], acc[ai][bj][m][n], 0, 0, 0); __builtin_amdgcn_s_setprio(0); } while (0)
; #define PG8_WAIT_V(n) asm volatile("s_waitcnt vmcnt(" #n ")" ::: "memory")
; #define PG8_WAIT_L(n) asm volatile("s_waitcnt lgkmcnt(" #n ")" ::: "memory")
; #define PG8_BAR __builtin_amdgcn_s_barrier()
; #define PG8_SCHED __builtin_amdgcn_sched_barrier(0)
; template <class Epi, class Sched, bool ALIGN_EPI = false, bool SP2 = false>
; __device__ __forceinline__ void gemm_phase(PG8_LAS unsigned char* lds, const Gemm g, const Sched& S, const Epi& E, int wave_in) {
;     ...
;             PG8_LDA(At, 1, 1); PG8_STAGE(PG8_SB(1, 0), b3, voffB); PG8_STAGE(PG8_SB(1, 1), b3 + hstep, voffB); PG8_STAGE(PG8_SA(1, 0), a3, voffA);
;             PG8_WAIT_V(8); PG8_WAIT_L(0); PG8_BAR; PG8_MMA(1, 0, At, B0); PG8_MMA(1, 1, At, B1); PG8_BAR; PG8_SCHED;
;     ...
;         if constexpr (ALIGN_EPI) { if (wr == 0) PG8_BAR; }
;         if constexpr (!Epi::AFTER_DRAIN) { E(acc, cur, wr, wc, fr, fq); S.done(cur); }
;         if (!has_next) break;
	s_add_i32 s4, s41, s24
	v_lshl_add_u64 v[156:157], v[156:157], 0, s[84:85]
	s_mov_b32 m0, s4
	ds_read_b128 v[188:191], v183 offset:49152
	ds_read_b128 v[212:215], v183 offset:50176
	ds_read_b128 v[216:219], v183 offset:51200
	ds_read_b128 v[220:223], v183 offset:52224
	ds_read_b128 v[224:227], v183 offset:53248
	ds_read_b128 v[228:231], v183 offset:54272
	ds_read_b128 v[232:235], v183 offset:55296
	ds_read_b128 v[236:239], v183 offset:56320
	global_load_lds_dwordx4 v[156:157], off
	s_add_i32 m0, s4, 0x2000
	s_add_u32 s2, s2, 0x80080
	v_lshl_add_u64 v[156:157], v[192:193], 0, s[84:85]
	s_addc_u32 s3, s3, 0
	s_add_i32 s4, s42, s24
	global_load_lds_dwordx4 v[156:157], off
	v_lshl_add_u64 v[156:157], s[2:3], 0, v[0:1]
	s_mov_b32 m0, s4
	s_nop 0
	global_load_lds_dwordx4 v[156:157], off
	v_lshl_add_u64 v[156:157], s[2:3], 0, v[146:147]
	s_add_i32 m0, s4, 0x2000
	s_nop 0
	global_load_lds_dwordx4 v[156:157], off
	v_lshl_add_u64 v[156:157], v[240:241], 0, s[84:85]
	s_mov_b32 m0, s29
	s_nop 0
	global_load_lds_dwordx4 v[156:157], off
	v_lshl_add_u64 v[156:157], v[242:243], 0, s[84:85]
	s_mov_b32 m0, s30
	s_nop 0
	global_load_lds_dwordx4 v[156:157], off
	s_waitcnt vmcnt(8) lgkmcnt(0)
	s_barrier
	v_mfma_f32_16x16x32_bf16 v[78:81], v[50:53], v[188:191], v[78:81]
	v_mfma_f32_16x16x32_bf16 v[74:77], v[66:69], v[188:191], v[74:77]
	v_mfma_f32_16x16x32_bf16 v[62:65], v[50:53], v[216:219], v[62:65]
	v_mfma_f32_16x16x32_bf16 v[58:61], v[66:69], v[216:219], v[58:61]
	v_mfma_f32_16x16x32_bf16 v[38:41], v[50:53], v[224:227], v[38:41]
	v_mfma_f32_16x16x32_bf16 v[34:37], v[66:69], v[224:227], v[34:37]
	v_mfma_f32_16x16x32_bf16 v[14:17], v[50:53], v[232:235], v[14:17]
	v_mfma_f32_16x16x32_bf16 v[10:13], v[66:69], v[232:235], v[10:13]
	v_mfma_f32_16x16x32_bf16 v[78:81], v[54:57], v[212:215], v[78:81]
	v_mfma_f32_16x16x32_bf16 v[74:77], v[70:73], v[212:215], v[74:77]
	v_mfma_f32_16x16x32_bf16 v[62:65], v[54:57], v[220:223], v[62:65]
	v_mfma_f32_16x16x32_bf16 v[58:61], v[70:73], v[220:223], v[58:61]
	v_mfma_f32_16x16x32_bf16 v[38:41], v[54:57], v[228:231], v[38:41]
	v_mfma_f32_16x16x32_bf16 v[34:37], v[70:73], v[228:231], v[34:37]
	v_mfma_f32_16x16x32_bf16 v[14:17], v[54:57], v[236:239], v[14:17]
	v_mfma_f32_16x16x32_bf16 v[10:13], v[70:73], v[236:239], v[10:13]
	v_mfma_f32_16x16x32_bf16 v[26:29], v[168:171], v[188:191], v[26:29]
	v_mfma_f32_16x16x32_bf16 v[70:73], v[172:175], v[212:215], v[26:29]
	v_mfma_f32_16x16x32_bf16 v[26:29], v[176:179], v[188:191], v[30:33]
	v_mfma_f32_16x16x32_bf16 v[66:69], v[184:187], v[212:215], v[26:29]
	v_mfma_f32_16x16x32_bf16 v[26:29], v[168:171], v[216:219], v[42:45]
	v_mfma_f32_16x16x32_bf16 v[54:57], v[172:175], v[220:223], v[26:29]
	v_mfma_f32_16x16x32_bf16 v[26:29], v[176:179], v[216:219], v[46:49]
	v_mfma_f32_16x16x32_bf16 v[22:25], v[168:171], v[224:227], v[22:25]
	v_mfma_f32_16x16x32_bf16 v[18:21], v[176:179], v[224:227], v[18:21]
	v_mfma_f32_16x16x32_bf16 v[6:9], v[168:171], v[232:235], v[6:9]
	v_mfma_f32_16x16x32_bf16 v[2:5], v[176:179], v[232:235], v[2:5]
	v_mfma_f32_16x16x32_bf16 v[50:53], v[184:187], v[220:223], v[26:29]
	v_mfma_f32_16x16x32_bf16 v[22:25], v[172:175], v[228:231], v[22:25]
	v_mfma_f32_16x16x32_bf16 v[18:21], v[184:187], v[228:231], v[18:21]
	v_mfma_f32_16x16x32_bf16 v[6:9], v[172:175], v[236:239], v[6:9]
	v_mfma_f32_16x16x32_bf16 v[2:5], v[184:187], v[236:239], v[2:5]
	s_barrier
	s_add_i32 s40, s40, 2
	s_add_u32 s0, s0, 0x100
	s_addc_u32 s1, s1, 0
	s_add_u32 s38, s38, 0x100
	s_addc_u32 s39, s39, 0
	s_cmp_gt_u32 s40, 29
	s_cbranch_scc0 .LBB0_277
	s_and_b64 vcc, exec, s[14:15]
	s_cbranch_vccz .LBB0_280
	s_barrier

; #define PG8_STAGE(bufoff, gbase, voff) do { _Pragma("unroll") for (int _i = 0; _i < 2; ++_i) \
;         __builtin_amdgcn_global_load_lds((const unsigned*)((const char*)(gbase) + (voff)[_i]), (PG8_LAS unsigned*)(lds + (bufoff) + ldsw + _i * 8192), 16, 0, 0); } while (0)
; #define PG8_LDA(dst, b, h) do { _Pragma("unroll") for (int m = 0; m < 4; ++m) _Pragma("unroll") for (int k = 0; k < 2; ++k) dst[m][k] = *(const PG8_LAS bf16x8*)(lds + PG8_SA(b, h) + aoff + m * 2048 + k * 1024); } while (0)
; #define PG8_LDB(dst, b, h) do { _Pragma("unroll") for (int n = 0; n < 2; ++n) _Pragma("unroll") for (int k = 0; k < 2; ++k) dst[n][k] = *(const PG8_LAS bf16x8*)(lds + PG8_SB(b, h) + boff + n * 2048 + k * 1024); } while (0)
; #define PG8_MMA(ai, bj, At, Bt) do { __builtin_amdgcn_s_setprio(1); _Pragma("unroll") for (int m = 0; m < 4; ++m) _Pragma("unroll") for (int n = 0; n < 2; ++n) _Pragma("unroll") for (int k = 0; k < 2; ++k) \
;         acc[ai][bj][m][n] = __builtin_amdgcn_mfma_f32_16x16x32_bf16(Bt[n][k], At[m][k], acc[ai][bj][m][n], 0, 0, 0); __builtin_amdgcn_s_setprio(0); } while (0)
; #define PG8_WAIT_V(n) asm volatile("s_waitcnt vmcnt(" #n ")" ::: "memory")
; #define PG8_WAIT_L(n) asm volatile("s_waitcnt lgkmcnt(" #n ")" ::: "memory")
; template <class Epi, class Sched, bool ALIGN_EPI = false, bool SP2 = false>
; __device__ __forceinline__ void gemm_phase(PG8_LAS unsigned char* lds, const Gemm g, const Sched& S, const Epi& E, int wave_in) {
;     ...
;             const bool last = (t == nt - 2);
;             const char* a1 = cA + (size_t)(t + 1) * kstep;
;             const char* a2 = last ? nA : cA + (size_t)(t + 2) * kstep; const char* b2 = last ? nB : cB + (size_t)(t + 2) * kstep;
;             const char* a3 = a2 + kstep; const char* b3 = b2 + kstep;
;             if (last && has_next) S.a_ready(nxt);
;             if constexpr (SP2) {
;             PG8_LDB(B0, 0, 0); PG8_LDB(B1, 0, 1); PG8_SCHED; PG8_LDA(At, 0, 0); PG8_STAGE(PG8_SA(1, 1), a1 + hstepA, voffA);
;             PG8_WAIT_V(8); PG8_WAIT_L(0); PG8_BAR; PG8_MMA(0, 0, At, B0); PG8_MMA(0, 1, At, B1); PG8_BAR; PG8_SCHED;
;             PG8_LDA(At, 0, 1); PG8_STAGE(PG8_SB(0, 0), b2, voffB); PG8_STAGE(PG8_SB(0, 1), b2 + hstep, voffB); PG8_STAGE(PG8_SA(0, 0), a2, voffA);
;             PG8_WAIT_V(8); PG8_WAIT_L(0); PG8_BAR; PG8_MMA(1, 0, At, B0); PG8_MMA(1, 1, At, B1); PG8_BAR; PG8_SCHED;
.Lmg_nohook:
	s_add_i32 s43, s6, 2
	s_add_u32 s44, s4, 0x80
	s_addc_u32 s7, s5, 0
	s_add_i32 s46, 0, 0x10000
	s_cmp_eq_u32 s37, s6
	s_cselect_b32 s7, s21, s7
	s_cselect_b32 s6, s20, s44
	s_cselect_b32 s45, s23, s25
	s_cselect_b32 s44, s22, s24
	s_add_i32 s47, 0, 0x14000
	v_add_u32_e32 v168, s46, v149
	v_add_u32_e32 v184, s47, v149
	ds_read_b128 v[140:143], v168
	ds_read_b128 v[144:147], v168 offset:1024
	ds_read_b128 v[154:157], v168 offset:2048
	ds_read_b128 v[168:171], v168 offset:3072
	ds_read_b128 v[172:175], v184
	ds_read_b128 v[176:179], v184 offset:1024
	ds_read_b128 v[180:183], v184 offset:2048
	ds_read_b128 v[184:187], v184 offset:3072
	v_lshl_add_u64 v[192:193], s[4:5], 0, v[136:137]
	s_add_i32 m0, s28, 0xc000
	ds_read_b128 v[188:191], v153
	ds_read_b128 v[212:215], v153 offset:1024
	ds_read_b128 v[216:219], v153 offset:2048
	ds_read_b128 v[220:223], v153 offset:3072
	ds_read_b128 v[224:227], v153 offset:4096
	ds_read_b128 v[228:231], v153 offset:5120
	ds_read_b128 v[232:235], v153 offset:6144
	ds_read_b128 v[236:239], v153 offset:7168
	global_load_lds_dwordx4 v[192:193], off
	v_lshl_add_u64 v[192:193], s[4:5], 0, v[138:139]
	s_add_i32 m0, s28, 0xe000
	s_nop 0
	global_load_lds_dwordx4 v[192:193], off
	s_waitcnt vmcnt(8) lgkmcnt(0)
	s_barrier
	v_mfma_f32_16x16x32_bf16 v[126:129], v[140:143], v[188:191], v[126:129]
	v_mfma_f32_16x16x32_bf16 v[122:125], v[154:157], v[188:191], v[122:125]
	v_mfma_f32_16x16x32_bf16 v[110:113], v[140:143], v[216:219], v[110:113]
	v_mfma_f32_16x16x32_bf16 v[106:109], v[154:157], v[216:219], v[106:109]
	v_mfma_f32_16x16x32_bf16 v[94:97], v[140:143], v[224:227], v[94:97]
	v_mfma_f32_16x16x32_bf16 v[90:93], v[154:157], v[224:227], v[90:93]
	v_mfma_f32_16x16x32_bf16 v[78:81], v[140:143], v[232:235], v[78:81]
	v_mfma_f32_16x16x32_bf16 v[74:77], v[154:157], v[232:235], v[74:77]
	v_mfma_f32_16x16x32_bf16 v[126:129], v[144:147], v[212:215], v[126:129]
	v_mfma_f32_16x16x32_bf16 v[122:125], v[168:171], v[212:215], v[122:125]
	v_mfma_f32_16x16x32_bf16 v[110:113], v[144:147], v[220:223], v[110:113]
	v_mfma_f32_16x16x32_bf16 v[106:109], v[168:171], v[220:223], v[106:109]
	v_mfma_f32_16x16x32_bf16 v[94:97], v[144:147], v[228:231], v[94:97]
	v_mfma_f32_16x16x32_bf16 v[90:93], v[168:171], v[228:231], v[90:93]
	v_mfma_f32_16x16x32_bf16 v[78:81], v[144:147], v[236:239], v[78:81]
	v_mfma_f32_16x16x32_bf16 v[74:77], v[168:171], v[236:239], v[74:77]
	v_mfma_f32_16x16x32_bf16 v[118:121], v[172:175], v[188:191], v[118:121]
	v_mfma_f32_16x16x32_bf16 v[114:117], v[180:183], v[188:191], v[114:117]
	v_mfma_f32_16x16x32_bf16 v[102:105], v[172:175], v[216:219], v[102:105]
	v_mfma_f32_16x16x32_bf16 v[98:101], v[180:183], v[216:219], v[98:101]
	v_mfma_f32_16x16x32_bf16 v[86:89], v[172:175], v[224:227], v[86:89]
	v_mfma_f32_16x16x32_bf16 v[82:85], v[180:183], v[224:227], v[82:85]
	v_mfma_f32_16x16x32_bf16 v[70:73], v[172:175], v[232:235], v[70:73]
	v_mfma_f32_16x16x32_bf16 v[66:69], v[180:183], v[232:235], v[66:69]
	v_mfma_f32_16x16x32_bf16 v[118:121], v[176:179], v[212:215], v[118:121]
	v_mfma_f32_16x16x32_bf16 v[114:117], v[184:187], v[212:215], v[114:117]
	v_mfma_f32_16x16x32_bf16 v[102:105], v[176:179], v[220:223], v[102:105]
	v_mfma_f32_16x16x32_bf16 v[98:101], v[184:187], v[220:223], v[98:101]
	v_mfma_f32_16x16x32_bf16 v[86:89], v[176:179], v[228:231], v[86:89]
	v_mfma_f32_16x16x32_bf16 v[82:85], v[184:187], v[228:231], v[82:85]
	v_mfma_f32_16x16x32_bf16 v[70:73], v[176:179], v[236:239], v[70:73]
	v_mfma_f32_16x16x32_bf16 v[66:69], v[184:187], v[236:239], v[66:69]
	s_barrier
	s_add_i32 s46, s46, s27
	v_lshl_add_u64 v[192:193], s[44:45], 0, v[0:1]
	s_mov_b32 m0, s46
	ds_read_b128 v[188:191], v153 offset:16384
	ds_read_b128 v[212:215], v153 offset:17408
	ds_read_b128 v[216:219], v153 offset:18432
	ds_read_b128 v[220:223], v153 offset:19456
	ds_read_b128 v[224:227], v153 offset:20480
	ds_read_b128 v[228:231], v153 offset:21504
	ds_read_b128 v[232:235], v153 offset:22528
	ds_read_b128 v[236:239], v153 offset:23552
	global_load_lds_dwordx4 v[192:193], off
	s_add_i32 m0, s46, 0x2000
	v_lshl_add_u64 v[200:201], s[44:45], 0, v[130:131]
	s_add_u32 s44, s44, s78
	s_addc_u32 s45, s45, 0
	s_add_i32 s46, s47, s27
	global_load_lds_dwordx4 v[200:201], off
	v_lshl_add_u64 v[240:241], s[44:45], 0, v[0:1]
	s_mov_b32 m0, s46
	v_lshl_add_u64 v[242:243], s[44:45], 0, v[130:131]
	global_load_lds_dwordx4 v[240:241], off
	s_add_i32 m0, s46, 0x2000
	v_lshl_add_u64 v[244:245], s[6:7], 0, v[134:135]
	global_load_lds_dwordx4 v[242:243], off
	s_mov_b32 m0, s28
	v_lshl_add_u64 v[246:247], s[6:7], 0, v[132:133]
	global_load_lds_dwordx4 v[244:245], off
	s_mov_b32 m0, s29
	s_nop 0
	global_load_lds_dwordx4 v[246:247], off
	s_waitcnt vmcnt(8) lgkmcnt(0)
	s_barrier
; #define PG8_STAGE(bufoff, gbase, voff) do { _Pragma("unroll") for (int _i = 0; _i < 2; ++_i) \
;         __builtin_amdgcn_global_load_lds((const unsigned*)((const char*)(gbase) + (voff)[_i]), (PG8_LAS unsigned*)(lds + (bufoff) + ldsw + _i * 8192), 16, 0, 0); } while (0)
; #define PG8_LDA(dst, b, h) do { _Pragma("unroll") for (int m = 0; m < 4; ++m) _Pragma("unroll") for (int k = 0; k < 2; ++k) dst[m][k] = *(const PG8_LAS bf16x8*)(lds + PG8_SA(b, h) + aoff + m * 2048 + k * 1024); } while (0)
; #define PG8_LDB(dst, b, h) do { _Pragma("unroll") for (int n = 0; n < 2; ++n) _Pragma("unroll") for (int k = 0; k < 2; ++k) dst[n][k] = *(const PG8_LAS bf16x8*)(lds + PG8_SB(b, h) + boff + n * 2048 + k * 1024); } while (0)
; #define PG8_MMA(ai, bj, At, Bt) do { __builtin_amdgcn_s_setprio(1); _Pragma("unroll") for (int m = 0; m < 4; ++m) _Pragma("unroll") for (int n = 0; n < 2; ++n) _Pragma("unroll") for (int k = 0; k < 2; ++k) \
;         acc[ai][bj][m][n] = __builtin_amdgcn_mfma_f32_16x16x32_bf16(Bt[n][k], At[m][k], acc[ai][bj][m][n], 0, 0, 0); __builtin_amdgcn_s_setprio(0); } while (0)
; #define PG8_WAIT_V(n) asm volatile("s_waitcnt vmcnt(" #n ")" ::: "memory")
; #define PG8_WAIT_L(n) asm volatile("s_waitcnt lgkmcnt(" #n ")" ::: "memory")
; #define PG8_BAR __builtin_amdgcn_s_barrier()
; #define PG8_SCHED __builtin_amdgcn_sched_barrier(0)
; template <class Epi, class Sched, bool ALIGN_EPI = false, bool SP2 = false>
; __device__ __forceinline__ void gemm_phase(PG8_LAS unsigned char* lds, const Gemm g, const Sched& S, const Epi& E, int wave_in) {
;     ...
;             PG8_WAIT_V(8); PG8_WAIT_L(0); PG8_BAR; PG8_MMA(1, 0, At, B0); PG8_MMA(1, 1, At, B1); PG8_BAR; PG8_SCHED;
;             PG8_LDB(B0, 1, 0); PG8_LDB(B1, 1, 1); PG8_SCHED; PG8_LDA(At, 1, 0); PG8_STAGE(PG8_SA(0, 1), a2 + hstepA, voffA);
;             PG8_WAIT_V(8); PG8_WAIT_L(0); PG8_BAR; PG8_MMA(0, 0, At, B0); PG8_MMA(0, 1, At, B1); PG8_BAR; PG8_SCHED;
	v_mfma_f32_16x16x32_bf16 v[62:65], v[140:143], v[188:191], v[62:65]
	v_mfma_f32_16x16x32_bf16 v[58:61], v[154:157], v[188:191], v[58:61]
	v_mfma_f32_16x16x32_bf16 v[46:49], v[140:143], v[216:219], v[46:49]
	v_mfma_f32_16x16x32_bf16 v[42:45], v[154:157], v[216:219], v[42:45]
	v_mfma_f32_16x16x32_bf16 v[30:33], v[140:143], v[224:227], v[30:33]
	v_mfma_f32_16x16x32_bf16 v[26:29], v[154:157], v[224:227], v[26:29]
	v_mfma_f32_16x16x32_bf16 v[14:17], v[140:143], v[232:235], v[14:17]
	v_mfma_f32_16x16x32_bf16 v[10:13], v[154:157], v[232:235], v[10:13]
	v_mfma_f32_16x16x32_bf16 v[62:65], v[144:147], v[212:215], v[62:65]
	v_mfma_f32_16x16x32_bf16 v[58:61], v[168:171], v[212:215], v[58:61]
	v_mfma_f32_16x16x32_bf16 v[46:49], v[144:147], v[220:223], v[46:49]
	v_mfma_f32_16x16x32_bf16 v[42:45], v[168:171], v[220:223], v[42:45]
	v_mfma_f32_16x16x32_bf16 v[30:33], v[144:147], v[228:231], v[30:33]
	v_mfma_f32_16x16x32_bf16 v[26:29], v[168:171], v[228:231], v[26:29]
	v_mfma_f32_16x16x32_bf16 v[14:17], v[144:147], v[236:239], v[14:17]
	v_mfma_f32_16x16x32_bf16 v[10:13], v[168:171], v[236:239], v[10:13]
	v_mfma_f32_16x16x32_bf16 v[54:57], v[172:175], v[188:191], v[54:57]
	v_mfma_f32_16x16x32_bf16 v[50:53], v[180:183], v[188:191], v[50:53]
	v_mfma_f32_16x16x32_bf16 v[38:41], v[172:175], v[216:219], v[38:41]
	v_mfma_f32_16x16x32_bf16 v[34:37], v[180:183], v[216:219], v[34:37]
	v_mfma_f32_16x16x32_bf16 v[22:25], v[172:175], v[224:227], v[22:25]
	v_mfma_f32_16x16x32_bf16 v[18:21], v[180:183], v[224:227], v[18:21]
	v_mfma_f32_16x16x32_bf16 v[6:9], v[172:175], v[232:235], v[6:9]
	v_mfma_f32_16x16x32_bf16 v[2:5], v[180:183], v[232:235], v[2:5]
	v_mfma_f32_16x16x32_bf16 v[54:57], v[176:179], v[212:215], v[54:57]
	v_mfma_f32_16x16x32_bf16 v[50:53], v[184:187], v[212:215], v[50:53]
	v_mfma_f32_16x16x32_bf16 v[38:41], v[176:179], v[220:223], v[38:41]
	v_mfma_f32_16x16x32_bf16 v[34:37], v[184:187], v[220:223], v[34:37]
	v_mfma_f32_16x16x32_bf16 v[22:25], v[176:179], v[228:231], v[22:25]
	v_mfma_f32_16x16x32_bf16 v[18:21], v[184:187], v[228:231], v[18:21]
	v_mfma_f32_16x16x32_bf16 v[6:9], v[176:179], v[236:239], v[6:9]
	v_mfma_f32_16x16x32_bf16 v[2:5], v[184:187], v[236:239], v[2:5]
	s_barrier
	s_add_i32 s44, 0, 0x18000
	s_add_i32 s45, 0, 0x1c000
	v_add_u32_e32 v168, s44, v149
	v_add_u32_e32 v184, s45, v149
	ds_read_b128 v[140:143], v168
	ds_read_b128 v[144:147], v168 offset:1024
	ds_read_b128 v[154:157], v168 offset:2048
	ds_read_b128 v[168:171], v168 offset:3072
	ds_read_b128 v[172:175], v184
	ds_read_b128 v[176:179], v184 offset:1024
	ds_read_b128 v[180:183], v184 offset:2048
	ds_read_b128 v[184:187], v184 offset:3072
	s_add_u32 s6, s6, s78
	s_addc_u32 s7, s7, 0
	s_mov_b32 m0, s30
	v_lshl_add_u64 v[248:249], s[6:7], 0, v[134:135]
	ds_read_b128 v[188:191], v153 offset:32768
	ds_read_b128 v[212:215], v153 offset:33792
	ds_read_b128 v[216:219], v153 offset:34816
	ds_read_b128 v[220:223], v153 offset:35840
	ds_read_b128 v[224:227], v153 offset:36864
	ds_read_b128 v[228:231], v153 offset:37888
	ds_read_b128 v[232:235], v153 offset:38912
	ds_read_b128 v[236:239], v153 offset:39936
	global_load_lds_dwordx4 v[248:249], off
	v_lshl_add_u64 v[248:249], s[6:7], 0, v[132:133]
	s_mov_b32 m0, s31
	s_nop 0
	global_load_lds_dwordx4 v[248:249], off
	s_waitcnt vmcnt(8) lgkmcnt(0)
	s_barrier
	v_mfma_f32_16x16x32_bf16 v[126:129], v[140:143], v[188:191], v[126:129]
	v_mfma_f32_16x16x32_bf16 v[122:125], v[154:157], v[188:191], v[122:125]
	v_mfma_f32_16x16x32_bf16 v[110:113], v[140:143], v[216:219], v[110:113]
	v_mfma_f32_16x16x32_bf16 v[106:109], v[154:157], v[216:219], v[106:109]
	v_mfma_f32_16x16x32_bf16 v[94:97], v[140:143], v[224:227], v[94:97]
	v_mfma_f32_16x16x32_bf16 v[90:93], v[154:157], v[224:227], v[90:93]
	v_mfma_f32_16x16x32_bf16 v[78:81], v[140:143], v[232:235], v[78:81]
	v_mfma_f32_16x16x32_bf16 v[74:77], v[154:157], v[232:235], v[74:77]
	v_mfma_f32_16x16x32_bf16 v[126:129], v[144:147], v[212:215], v[126:129]
	v_mfma_f32_16x16x32_bf16 v[122:125], v[168:171], v[212:215], v[122:125]
	v_mfma_f32_16x16x32_bf16 v[110:113], v[144:147], v[220:223], v[110:113]
	v_mfma_f32_16x16x32_bf16 v[106:109], v[168:171], v[220:223], v[106:109]
	v_mfma_f32_16x16x32_bf16 v[94:97], v[144:147], v[228:231], v[94:97]
	v_mfma_f32_16x16x32_bf16 v[90:93], v[168:171], v[228:231], v[90:93]
	v_mfma_f32_16x16x32_bf16 v[78:81], v[144:147], v[236:239], v[78:81]
	v_mfma_f32_16x16x32_bf16 v[74:77], v[168:171], v[236:239], v[74:77]
	v_mfma_f32_16x16x32_bf16 v[118:121], v[172:175], v[188:191], v[118:121]
	v_mfma_f32_16x16x32_bf16 v[114:117], v[180:183], v[188:191], v[114:117]
	v_mfma_f32_16x16x32_bf16 v[102:105], v[172:175], v[216:219], v[102:105]
	v_mfma_f32_16x16x32_bf16 v[98:101], v[180:183], v[216:219], v[98:101]
	v_mfma_f32_16x16x32_bf16 v[86:89], v[172:175], v[224:227], v[86:89]
	v_mfma_f32_16x16x32_bf16 v[82:85], v[180:183], v[224:227], v[82:85]
	v_mfma_f32_16x16x32_bf16 v[70:73], v[172:175], v[232:235], v[70:73]
	v_mfma_f32_16x16x32_bf16 v[66:69], v[180:183], v[232:235], v[66:69]
	v_mfma_f32_16x16x32_bf16 v[118:121], v[176:179], v[212:215], v[118:121]
	v_mfma_f32_16x16x32_bf16 v[114:117], v[184:187], v[212:215], v[114:117]
	v_mfma_f32_16x16x32_bf16 v[102:105], v[176:179], v[220:223], v[102:105]
	v_mfma_f32_16x16x32_bf16 v[98:101], v[184:187], v[220:223], v[98:101]
	v_mfma_f32_16x16x32_bf16 v[86:89], v[176:179], v[228:231], v[86:89]
	v_mfma_f32_16x16x32_bf16 v[82:85], v[184:187], v[228:231], v[82:85]
	v_mfma_f32_16x16x32_bf16 v[70:73], v[176:179], v[236:239], v[70:73]
	v_mfma_f32_16x16x32_bf16 v[66:69], v[184:187], v[236:239], v[66:69]
	s_barrier
; #define PG8_STAGE(bufoff, gbase, voff) do { _Pragma("unroll") for (int _i = 0; _i < 2; ++_i) \
;         __builtin_amdgcn_global_load_lds((const unsigned*)((const char*)(gbase) + (voff)[_i]), (PG8_LAS unsigned*)(lds + (bufoff) + ldsw + _i * 8192), 16, 0, 0); } while (0)
; #define PG8_LDA(dst, b, h) do { _Pragma("unroll") for (int m = 0; m < 4; ++m) _Pragma("unroll") for (int k = 0; k < 2; ++k) dst[m][k] = *(const PG8_LAS bf16x8*)(lds + PG8_SA(b, h) + aoff + m * 2048 + k * 1024); } while (0)
; #define PG8_MMA(ai, bj, At, Bt) do { __builtin_amdgcn_s_setprio(1); _Pragma("unroll") for (int m = 0; m < 4; ++m) _Pragma("unroll") for (int n = 0; n < 2; ++n) _Pragma("unroll") for (int k = 0; k < 2; ++k) \
;         acc[ai][bj][m][n] = __builtin_amdgcn_mfma_f32_16x16x32_bf16(Bt[n][k], At[m][k], acc[ai][bj][m][n], 0, 0, 0); __builtin_amdgcn_s_setprio(0); } while (0)
; #define PG8_WAIT_V(n) asm volatile("s_waitcnt vmcnt(" #n ")" ::: "memory")
; #define PG8_WAIT_L(n) asm volatile("s_waitcnt lgkmcnt(" #n ")" ::: "memory")
; #define PG8_BAR __builtin_amdgcn_s_barrier()
; #define PG8_SCHED __builtin_amdgcn_sched_barrier(0)
; template <class Epi, class Sched, bool ALIGN_EPI = false, bool SP2 = false>
; __device__ __forceinline__ void gemm_phase(PG8_LAS unsigned char* lds, const Gemm g, const Sched& S, const Epi& E, int wave_in) {
;     ...
;             PG8_LDA(At, 1, 1); PG8_STAGE(PG8_SB(1, 0), b3, voffB); PG8_STAGE(PG8_SB(1, 1), b3 + hstep, voffB); PG8_STAGE(PG8_SA(1, 0), a3, voffA);
;             PG8_WAIT_V(8); PG8_WAIT_L(0); PG8_BAR; PG8_MMA(1, 0, At, B0); PG8_MMA(1, 1, At, B1); PG8_BAR; PG8_SCHED;
;     ...
;         }
;         if constexpr (ALIGN_EPI) { if (wr == 0) PG8_BAR; }
;         if constexpr (!Epi::AFTER_DRAIN) { E(acc, cur, wr, wc, fr, fq); S.done(cur); }
;         if (!has_next) break;
	s_add_i32 s6, s44, s27
	v_lshl_add_u64 v[192:193], v[192:193], 0, s[84:85]
	s_mov_b32 m0, s6
	ds_read_b128 v[188:191], v153 offset:49152
	ds_read_b128 v[212:215], v153 offset:50176
	ds_read_b128 v[216:219], v153 offset:51200
	ds_read_b128 v[220:223], v153 offset:52224
	ds_read_b128 v[224:227], v153 offset:53248
	ds_read_b128 v[228:231], v153 offset:54272
	ds_read_b128 v[232:235], v153 offset:55296
	ds_read_b128 v[236:239], v153 offset:56320
	global_load_lds_dwordx4 v[192:193], off
	v_lshl_add_u64 v[192:193], v[200:201], 0, s[84:85]
	s_add_i32 m0, s6, 0x2000
	s_add_i32 s6, s45, s27
	global_load_lds_dwordx4 v[192:193], off
	v_lshl_add_u64 v[192:193], v[240:241], 0, s[84:85]
	s_mov_b32 m0, s6
	s_nop 0
	global_load_lds_dwordx4 v[192:193], off
	v_lshl_add_u64 v[192:193], v[242:243], 0, s[84:85]
	s_add_i32 m0, s6, 0x2000
	s_nop 0
	global_load_lds_dwordx4 v[192:193], off
	v_lshl_add_u64 v[192:193], v[244:245], 0, s[84:85]
	s_mov_b32 m0, s34
	s_nop 0
	global_load_lds_dwordx4 v[192:193], off
	v_lshl_add_u64 v[192:193], v[246:247], 0, s[84:85]
	s_mov_b32 m0, s35
	s_nop 0
	global_load_lds_dwordx4 v[192:193], off
	s_waitcnt vmcnt(8) lgkmcnt(0)
	s_barrier
	v_mfma_f32_16x16x32_bf16 v[62:65], v[140:143], v[188:191], v[62:65]
	v_mfma_f32_16x16x32_bf16 v[58:61], v[154:157], v[188:191], v[58:61]
	v_mfma_f32_16x16x32_bf16 v[46:49], v[140:143], v[216:219], v[46:49]
	v_mfma_f32_16x16x32_bf16 v[42:45], v[154:157], v[216:219], v[42:45]
	v_mfma_f32_16x16x32_bf16 v[30:33], v[140:143], v[224:227], v[30:33]
	v_mfma_f32_16x16x32_bf16 v[26:29], v[154:157], v[224:227], v[26:29]
	v_mfma_f32_16x16x32_bf16 v[14:17], v[140:143], v[232:235], v[14:17]
	v_mfma_f32_16x16x32_bf16 v[10:13], v[154:157], v[232:235], v[10:13]
	v_mfma_f32_16x16x32_bf16 v[62:65], v[144:147], v[212:215], v[62:65]
	v_mfma_f32_16x16x32_bf16 v[58:61], v[168:171], v[212:215], v[58:61]
	v_mfma_f32_16x16x32_bf16 v[46:49], v[144:147], v[220:223], v[46:49]
	v_mfma_f32_16x16x32_bf16 v[42:45], v[168:171], v[220:223], v[42:45]
	v_mfma_f32_16x16x32_bf16 v[30:33], v[144:147], v[228:231], v[30:33]
	v_mfma_f32_16x16x32_bf16 v[26:29], v[168:171], v[228:231], v[26:29]
	v_mfma_f32_16x16x32_bf16 v[14:17], v[144:147], v[236:239], v[14:17]
	v_mfma_f32_16x16x32_bf16 v[10:13], v[168:171], v[236:239], v[10:13]
	v_mfma_f32_16x16x32_bf16 v[54:57], v[172:175], v[188:191], v[54:57]
	v_mfma_f32_16x16x32_bf16 v[50:53], v[180:183], v[188:191], v[50:53]
	v_mfma_f32_16x16x32_bf16 v[38:41], v[172:175], v[216:219], v[38:41]
	v_mfma_f32_16x16x32_bf16 v[34:37], v[180:183], v[216:219], v[34:37]
	v_mfma_f32_16x16x32_bf16 v[22:25], v[172:175], v[224:227], v[22:25]
	v_mfma_f32_16x16x32_bf16 v[18:21], v[180:183], v[224:227], v[18:21]
	v_mfma_f32_16x16x32_bf16 v[6:9], v[172:175], v[232:235], v[6:9]
	v_mfma_f32_16x16x32_bf16 v[2:5], v[180:183], v[232:235], v[2:5]
	v_mfma_f32_16x16x32_bf16 v[54:57], v[176:179], v[212:215], v[54:57]
	v_mfma_f32_16x16x32_bf16 v[50:53], v[184:187], v[212:215], v[50:53]
	v_mfma_f32_16x16x32_bf16 v[38:41], v[176:179], v[220:223], v[38:41]
	v_mfma_f32_16x16x32_bf16 v[34:37], v[184:187], v[220:223], v[34:37]
	v_mfma_f32_16x16x32_bf16 v[22:25], v[176:179], v[228:231], v[22:25]
	v_mfma_f32_16x16x32_bf16 v[18:21], v[184:187], v[228:231], v[18:21]
	v_mfma_f32_16x16x32_bf16 v[6:9], v[176:179], v[236:239], v[6:9]
	v_mfma_f32_16x16x32_bf16 v[2:5], v[184:187], v[236:239], v[2:5]
	s_barrier
	s_add_u32 s4, s4, 0x100
	s_addc_u32 s5, s5, 0
	s_add_u32 s24, s24, 0x100
	s_addc_u32 s25, s25, 0
	s_cmp_ge_u32 s43, s36
	s_mov_b32 s6, s43
	s_cbranch_scc0 .LBB0_404
	s_and_b64 vcc, exec, s[16:17]
	s_cbranch_vccz .LBB0_407
	s_barrier
